# v24 + K-loop LDS-DMA issue 3/5/3/5 per phase (one piece of each A half-0 stage moved one phase later; waits 8/7/8/7)
# baseline (speedup 1.0000x reference)
; #define PG8_WAIT_V(n) asm volatile("s_waitcnt vmcnt(" #n ")" ::: "memory")
; template <class Epi, bool ALIGN_EPI, bool SP2, class Hook>
; __device__ __forceinline__ void gemm_phase(LAS unsigned char* lds, const Gemm g, const StaticOrder& S, const Epi& E, Acc& acc, const bool fresh, const Hook& H, const int wave_id) {
;     ...
;         if constexpr (SP2 && Epi::NSTORE > 0) {
;             const Src a1 = cA + kstep, a2 = cA + 2 * kstep, b2 = cB + 2 * kstep, a3 = a2 + kstep, b3 = b2 + kstep;
;             if constexpr (Epi::NSTORE == 16) PG8_TRIP_SP2(PG8_WAIT_V(24)); else PG8_TRIP_SP2(PG8_WAIT_V(16));
;             t0 = 2;
.LBB0_382:
	ds_read_b128 v[2:5], v150
	ds_read_b128 v[6:9], v150 offset:1024
	ds_read_b128 v[10:13], v150 offset:2048
	ds_read_b128 v[14:17], v150 offset:3072
	ds_read_b128 v[18:21], v151
	ds_read_b128 v[22:25], v151 offset:1024
	ds_read_b128 v[26:29], v151 offset:2048
	ds_read_b128 v[30:33], v151 offset:3072
	s_or_b32 s9, s68, 0x100
	s_or_b32 s8, s68, 0x180
	s_or_b32 s10, s69, 0x100
	s_or_b32 s11, s68, 0x40080
	s_mov_b32 m0, s45
	ds_read_b128 v[34:37], v149
	ds_read_b128 v[38:41], v149 offset:1024
	ds_read_b128 v[42:45], v149 offset:2048
	ds_read_b128 v[46:49], v149 offset:3072
	ds_read_b128 v[50:53], v149 offset:4096
	ds_read_b128 v[54:57], v149 offset:5120
	ds_read_b128 v[58:61], v149 offset:6144
	ds_read_b128 v[62:65], v149 offset:7168
	buffer_load_dwordx4 v144, s[0:3], s11 offen lds
	s_mov_b32 m0, s46
	s_nop 0
	buffer_load_dwordx4 v146, s[0:3], s11 offen lds
	s_waitcnt vmcnt(24)
	s_waitcnt lgkmcnt(0)
	s_setprio 1
	s_barrier
	v_mfma_f32_16x16x32_bf16 v[86:89], v[10:13], v[50:53], 0
	v_mfma_f32_16x16x32_bf16 v[92:95], v[14:17], v[54:57], v[86:89]
	v_mfma_f32_16x16x32_bf16 v[86:89], v[2:5], v[58:61], 0
	v_mfma_f32_16x16x32_bf16 v[66:69], v[2:5], v[34:37], 0
	v_mfma_f32_16x16x32_bf16 v[70:73], v[10:13], v[34:37], 0
	v_mfma_f32_16x16x32_bf16 v[74:77], v[2:5], v[42:45], 0
	v_mfma_f32_16x16x32_bf16 v[78:81], v[10:13], v[42:45], 0
	v_mfma_f32_16x16x32_bf16 v[82:85], v[2:5], v[50:53], 0
	v_mfma_f32_16x16x32_bf16 v[96:99], v[6:9], v[62:65], v[86:89]
	v_mfma_f32_16x16x32_bf16 v[86:89], v[10:13], v[58:61], 0
	v_mfma_f32_16x16x32_bf16 v[66:69], v[6:9], v[38:41], v[66:69]
	v_mfma_f32_16x16x32_bf16 v[70:73], v[14:17], v[38:41], v[70:73]
	v_mfma_f32_16x16x32_bf16 v[74:77], v[6:9], v[46:49], v[74:77]
	v_mfma_f32_16x16x32_bf16 v[78:81], v[14:17], v[46:49], v[78:81]
	v_mfma_f32_16x16x32_bf16 v[82:85], v[6:9], v[54:57], v[82:85]
	v_mfma_f32_16x16x32_bf16 v[104:107], v[14:17], v[62:65], v[86:89]
	v_mfma_f32_16x16x32_bf16 v[86:89], v[18:21], v[34:37], 0
	v_mfma_f32_16x16x32_bf16 v[34:37], v[26:29], v[34:37], 0
	v_mfma_f32_16x16x32_bf16 v[116:119], v[30:33], v[38:41], v[34:37]
	v_mfma_f32_16x16x32_bf16 v[34:37], v[18:21], v[42:45], 0
	v_mfma_f32_16x16x32_bf16 v[132:135], v[22:25], v[46:49], v[34:37]
	v_mfma_f32_16x16x32_bf16 v[34:37], v[26:29], v[42:45], 0
	v_mfma_f32_16x16x32_bf16 v[108:111], v[22:25], v[38:41], v[86:89]
	v_mfma_f32_16x16x32_bf16 v[40:43], v[30:33], v[46:49], v[34:37]
	v_mfma_f32_16x16x32_bf16 v[34:37], v[18:21], v[50:53], 0
	v_mfma_f32_16x16x32_bf16 v[44:47], v[22:25], v[54:57], v[34:37]
	v_mfma_f32_16x16x32_bf16 v[34:37], v[26:29], v[50:53], 0
	v_mfma_f32_16x16x32_bf16 v[48:51], v[30:33], v[54:57], v[34:37]
	v_mfma_f32_16x16x32_bf16 v[34:37], v[18:21], v[58:61], 0
	v_mfma_f32_16x16x32_bf16 v[52:55], v[22:25], v[62:65], v[34:37]
	v_mfma_f32_16x16x32_bf16 v[34:37], v[26:29], v[58:61], 0
	v_mfma_f32_16x16x32_bf16 v[60:63], v[30:33], v[62:65], v[34:37]
	s_barrier
	s_setprio 0
	s_mov_b32 m0, s92
	s_nop 3
	ds_read_b128 v[34:37], v149 offset:16384
	ds_read_b128 v[56:59], v149 offset:17408
	ds_read_b128 v[86:89], v149 offset:18432
	ds_read_b128 v[100:103], v149 offset:19456
	ds_read_b128 v[112:115], v149 offset:20480
	ds_read_b128 v[120:123], v149 offset:21504
	ds_read_b128 v[124:127], v149 offset:22528
	ds_read_b128 v[128:131], v149 offset:23552
	buffer_load_dwordx4 v145, s[4:7], s10 offen lds
	s_mov_b32 m0, s93
	s_nop 0
	buffer_load_dwordx4 v147, s[4:7], s10 offen lds
	s_or_b32 s10, s69, 0x40100
	s_mov_b32 m0, s94
	s_nop 0
	buffer_load_dwordx4 v145, s[4:7], s10 offen lds
	s_mov_b32 m0, s95
	s_nop 0
	buffer_load_dwordx4 v147, s[4:7], s10 offen lds
	s_mov_b32 m0, s44
	s_nop 0
	buffer_load_dwordx4 v144, s[0:3], s9 offen lds
	s_waitcnt vmcnt(23)
	s_waitcnt lgkmcnt(0)
	s_setprio 1
	s_barrier
	v_mfma_f32_16x16x32_bf16 v[136:139], v[2:5], v[34:37], 0
	v_mfma_f32_16x16x32_bf16 v[154:157], v[2:5], v[86:89], 0
	v_mfma_f32_16x16x32_bf16 v[162:165], v[2:5], v[112:115], 0
	v_mfma_f32_16x16x32_bf16 v[2:5], v[2:5], v[124:127], 0
	v_mfma_f32_16x16x32_bf16 v[136:139], v[6:9], v[56:59], v[136:139]
	v_mfma_f32_16x16x32_bf16 v[140:143], v[10:13], v[34:37], 0
	v_mfma_f32_16x16x32_bf16 v[154:157], v[6:9], v[100:103], v[154:157]
	v_mfma_f32_16x16x32_bf16 v[158:161], v[10:13], v[86:89], 0
	v_mfma_f32_16x16x32_bf16 v[162:165], v[6:9], v[120:123], v[162:165]
	v_mfma_f32_16x16x32_bf16 v[166:169], v[10:13], v[112:115], 0
	v_mfma_f32_16x16x32_bf16 v[2:5], v[6:9], v[128:131], v[2:5]
	v_mfma_f32_16x16x32_bf16 v[6:9], v[10:13], v[124:127], 0
	v_mfma_f32_16x16x32_bf16 v[140:143], v[14:17], v[56:59], v[140:143]
	v_mfma_f32_16x16x32_bf16 v[158:161], v[14:17], v[100:103], v[158:161]
	v_mfma_f32_16x16x32_bf16 v[166:169], v[14:17], v[120:123], v[166:169]
	v_mfma_f32_16x16x32_bf16 v[170:173], v[14:17], v[128:131], v[6:9]
	v_mfma_f32_16x16x32_bf16 v[6:9], v[18:21], v[34:37], 0
	v_mfma_f32_16x16x32_bf16 v[174:177], v[22:25], v[56:59], v[6:9]
	v_mfma_f32_16x16x32_bf16 v[6:9], v[26:29], v[34:37], 0
	v_mfma_f32_16x16x32_bf16 v[178:181], v[30:33], v[56:59], v[6:9]
	v_mfma_f32_16x16x32_bf16 v[6:9], v[18:21], v[86:89], 0
	v_mfma_f32_16x16x32_bf16 v[182:185], v[22:25], v[100:103], v[6:9]
	v_mfma_f32_16x16x32_bf16 v[6:9], v[26:29], v[86:89], 0
	v_mfma_f32_16x16x32_bf16 v[186:189], v[30:33], v[100:103], v[6:9]
	v_mfma_f32_16x16x32_bf16 v[6:9], v[18:21], v[112:115], 0
	v_mfma_f32_16x16x32_bf16 v[190:193], v[22:25], v[120:123], v[6:9]
	v_mfma_f32_16x16x32_bf16 v[6:9], v[26:29], v[112:115], 0
	v_mfma_f32_16x16x32_bf16 v[212:215], v[30:33], v[120:123], v[6:9]
	v_mfma_f32_16x16x32_bf16 v[6:9], v[18:21], v[124:127], 0
	v_mfma_f32_16x16x32_bf16 v[20:23], v[22:25], v[128:131], v[6:9]
	v_mfma_f32_16x16x32_bf16 v[6:9], v[26:29], v[124:127], 0
	v_mfma_f32_16x16x32_bf16 v[216:219], v[30:33], v[128:131], v[6:9]
	s_barrier
; #define PG8_WAIT_V(n) asm volatile("s_waitcnt vmcnt(" #n ")" ::: "memory")
; template <class Epi, bool ALIGN_EPI, bool SP2, class Hook>
; __device__ __forceinline__ void gemm_phase(LAS unsigned char* lds, const Gemm g, const StaticOrder& S, const Epi& E, Acc& acc, const bool fresh, const Hook& H, const int wave_id) {
;     ...
;         if constexpr (SP2 && Epi::NSTORE > 0) {
;             const Src a1 = cA + kstep, a2 = cA + 2 * kstep, b2 = cB + 2 * kstep, a3 = a2 + kstep, b3 = b2 + kstep;
;             if constexpr (Epi::NSTORE == 16) PG8_TRIP_SP2(PG8_WAIT_V(24)); else PG8_TRIP_SP2(PG8_WAIT_V(16));
;             t0 = 2;
	s_setprio 0
	s_mov_b32 m0, s36
	s_nop 0
	buffer_load_dwordx4 v146, s[0:3], s9 offen lds
	s_nop 4
	ds_read_b128 v[6:9], v152
	ds_read_b128 v[24:27], v152 offset:1024
	ds_read_b128 v[228:231], v152 offset:2048
	ds_read_b128 v[232:235], v152 offset:3072
	ds_read_b128 v[236:239], v153
	ds_read_b128 v[240:243], v153 offset:1024
	ds_read_b128 v[244:247], v153 offset:2048
	ds_read_b128 v[150:153], v153 offset:3072
	s_or_b32 s9, s68, 0x40100
	s_mov_b32 m0, s37
	ds_read_b128 v[10:13], v149 offset:32768
	ds_read_b128 v[14:17], v149 offset:33792
	ds_read_b128 v[32:35], v149 offset:34816
	ds_read_b128 v[194:197], v149 offset:35840
	ds_read_b128 v[208:211], v149 offset:36864
	ds_read_b128 v[200:203], v149 offset:37888
	ds_read_b128 v[204:207], v149 offset:38912
	ds_read_b128 v[220:223], v149 offset:39936
	buffer_load_dwordx4 v144, s[0:3], s9 offen lds
	s_mov_b32 m0, s38
	s_nop 0
	buffer_load_dwordx4 v146, s[0:3], s9 offen lds
	s_waitcnt vmcnt(8)
	s_waitcnt lgkmcnt(0)
	s_setprio 1
	s_barrier
	v_mfma_f32_16x16x32_bf16 v[28:31], v[6:9], v[10:13], v[66:69]
	v_mfma_f32_16x16x32_bf16 v[120:123], v[24:27], v[14:17], v[28:31]
	v_mfma_f32_16x16x32_bf16 v[28:31], v[228:231], v[10:13], v[70:73]
	v_mfma_f32_16x16x32_bf16 v[112:115], v[232:235], v[14:17], v[28:31]
	v_mfma_f32_16x16x32_bf16 v[28:31], v[6:9], v[32:35], v[74:77]
	v_mfma_f32_16x16x32_bf16 v[100:103], v[24:27], v[194:197], v[28:31]
	v_mfma_f32_16x16x32_bf16 v[28:31], v[228:231], v[32:35], v[78:81]
	v_mfma_f32_16x16x32_bf16 v[88:91], v[232:235], v[194:197], v[28:31]
	v_mfma_f32_16x16x32_bf16 v[28:31], v[6:9], v[208:211], v[82:85]
	v_mfma_f32_16x16x32_bf16 v[68:71], v[24:27], v[200:203], v[28:31]
	v_mfma_f32_16x16x32_bf16 v[28:31], v[228:231], v[208:211], v[92:95]
	v_mfma_f32_16x16x32_bf16 v[56:59], v[232:235], v[200:203], v[28:31]
	v_mfma_f32_16x16x32_bf16 v[28:31], v[6:9], v[204:207], v[96:99]
	v_mfma_f32_16x16x32_bf16 v[36:39], v[24:27], v[220:223], v[28:31]
	v_mfma_f32_16x16x32_bf16 v[28:31], v[228:231], v[204:207], v[104:107]
	v_mfma_f32_16x16x32_bf16 v[28:31], v[232:235], v[220:223], v[28:31]
	v_mfma_f32_16x16x32_bf16 v[64:67], v[236:239], v[10:13], v[108:111]
	v_mfma_f32_16x16x32_bf16 v[10:13], v[244:247], v[10:13], v[116:119]
	v_mfma_f32_16x16x32_bf16 v[124:127], v[150:153], v[14:17], v[10:13]
	v_mfma_f32_16x16x32_bf16 v[10:13], v[236:239], v[32:35], v[132:135]
	v_mfma_f32_16x16x32_bf16 v[116:119], v[240:243], v[194:197], v[10:13]
	v_mfma_f32_16x16x32_bf16 v[10:13], v[244:247], v[32:35], v[40:43]
	v_mfma_f32_16x16x32_bf16 v[108:111], v[150:153], v[194:197], v[10:13]
	v_mfma_f32_16x16x32_bf16 v[10:13], v[236:239], v[208:211], v[44:47]
	v_mfma_f32_16x16x32_bf16 v[92:95], v[240:243], v[200:203], v[10:13]
	v_mfma_f32_16x16x32_bf16 v[10:13], v[244:247], v[208:211], v[48:51]
	v_mfma_f32_16x16x32_bf16 v[80:83], v[150:153], v[200:203], v[10:13]
	v_mfma_f32_16x16x32_bf16 v[10:13], v[236:239], v[204:207], v[52:55]
	v_mfma_f32_16x16x32_bf16 v[128:131], v[240:243], v[14:17], v[64:67]
	v_mfma_f32_16x16x32_bf16 v[64:67], v[240:243], v[220:223], v[10:13]
	v_mfma_f32_16x16x32_bf16 v[10:13], v[244:247], v[204:207], v[60:63]
	v_mfma_f32_16x16x32_bf16 v[48:51], v[150:153], v[220:223], v[10:13]
	s_barrier
	s_setprio 0
	s_mov_b32 m0, s39
	s_or_b32 s9, s69, 0x180
	ds_read_b128 v[44:47], v149 offset:49152
	ds_read_b128 v[52:55], v149 offset:50176
	ds_read_b128 v[76:79], v149 offset:51200
	ds_read_b128 v[132:135], v149 offset:52224
	ds_read_b128 v[194:197], v149 offset:53248
	ds_read_b128 v[200:203], v149 offset:54272
	ds_read_b128 v[204:207], v149 offset:55296
	ds_read_b128 v[208:211], v149 offset:56320
	buffer_load_dwordx4 v145, s[4:7], s9 offen lds
	s_mov_b32 m0, s40
	s_nop 0
	buffer_load_dwordx4 v147, s[4:7], s9 offen lds
	s_or_b32 s9, s69, 0x40180
	s_mov_b32 m0, s43
	s_nop 0
	buffer_load_dwordx4 v145, s[4:7], s9 offen lds
	s_mov_b32 m0, s42
	s_nop 0
	buffer_load_dwordx4 v147, s[4:7], s9 offen lds
	s_mov_b32 m0, s41
	s_nop 0
	buffer_load_dwordx4 v144, s[0:3], s8 offen lds
	s_waitcnt vmcnt(7)
	s_waitcnt lgkmcnt(0)
	s_setprio 1
	s_barrier
	v_mfma_f32_16x16x32_bf16 v[10:13], v[6:9], v[44:47], v[136:139]
	v_mfma_f32_16x16x32_bf16 v[72:75], v[24:27], v[52:55], v[10:13]
	v_mfma_f32_16x16x32_bf16 v[10:13], v[228:231], v[44:47], v[140:143]
	v_mfma_f32_16x16x32_bf16 v[60:63], v[232:235], v[52:55], v[10:13]
	v_mfma_f32_16x16x32_bf16 v[10:13], v[6:9], v[76:79], v[154:157]
	v_mfma_f32_16x16x32_bf16 v[40:43], v[24:27], v[132:135], v[10:13]
	v_mfma_f32_16x16x32_bf16 v[10:13], v[228:231], v[76:79], v[158:161]
	v_mfma_f32_16x16x32_bf16 v[32:35], v[232:235], v[132:135], v[10:13]
	v_mfma_f32_16x16x32_bf16 v[10:13], v[6:9], v[194:197], v[162:165]
	v_mfma_f32_16x16x32_bf16 v[16:19], v[24:27], v[200:203], v[10:13]
	v_mfma_f32_16x16x32_bf16 v[10:13], v[228:231], v[194:197], v[166:169]
	v_mfma_f32_16x16x32_bf16 v[2:5], v[6:9], v[204:207], v[2:5]
	v_mfma_f32_16x16x32_bf16 v[12:15], v[232:235], v[200:203], v[10:13]
	v_mfma_f32_16x16x32_bf16 v[8:11], v[24:27], v[208:211], v[2:5]
	v_mfma_f32_16x16x32_bf16 v[2:5], v[228:231], v[204:207], v[170:173]
	v_mfma_f32_16x16x32_bf16 v[4:7], v[232:235], v[208:211], v[2:5]
	v_mfma_f32_16x16x32_bf16 v[24:27], v[236:239], v[44:47], v[174:177]
	v_mfma_f32_16x16x32_bf16 v[96:99], v[240:243], v[52:55], v[24:27]
	v_mfma_f32_16x16x32_bf16 v[24:27], v[244:247], v[44:47], v[178:181]
	v_mfma_f32_16x16x32_bf16 v[104:107], v[150:153], v[52:55], v[24:27]
	v_mfma_f32_16x16x32_bf16 v[24:27], v[236:239], v[76:79], v[182:185]
	v_mfma_f32_16x16x32_bf16 v[84:87], v[240:243], v[132:135], v[24:27]
	v_mfma_f32_16x16x32_bf16 v[24:27], v[244:247], v[76:79], v[186:189]
	v_mfma_f32_16x16x32_bf16 v[76:79], v[150:153], v[132:135], v[24:27]
	v_mfma_f32_16x16x32_bf16 v[24:27], v[236:239], v[194:197], v[190:193]
	v_mfma_f32_16x16x32_bf16 v[52:55], v[240:243], v[200:203], v[24:27]
	v_mfma_f32_16x16x32_bf16 v[24:27], v[244:247], v[194:197], v[212:215]
	v_mfma_f32_16x16x32_bf16 v[20:23], v[236:239], v[204:207], v[20:23]
	v_mfma_f32_16x16x32_bf16 v[44:47], v[150:153], v[200:203], v[24:27]
	v_mfma_f32_16x16x32_bf16 v[24:27], v[240:243], v[208:211], v[20:23]
	v_mfma_f32_16x16x32_bf16 v[20:23], v[244:247], v[204:207], v[216:219]
	v_mfma_f32_16x16x32_bf16 v[20:23], v[150:153], v[208:211], v[20:23]
	s_barrier
	s_setprio 0
	s_mov_b64 s[8:9], 0
	v_mov_b64_e32 v[234:235], v[198:199]
	v_mov_b64_e32 v[236:237], v[226:227]
	v_mov_b32_e32 v198, v0
	v_mov_b32_e32 v226, v225
	v_mov_b64_e32 v[244:245], 0x100
	v_mov_b64_e32 v[246:247], 0xff

; #define PG8_WAIT_V(n) asm volatile("s_waitcnt vmcnt(" #n ")" ::: "memory")
; template <class Epi, bool ALIGN_EPI, bool SP2, class Hook>
; __device__ __forceinline__ void gemm_phase(LAS unsigned char* lds, const Gemm g, const StaticOrder& S, const Epi& E, Acc& acc, const bool fresh, const Hook& H, const int wave_id) {
;     ...
;         for (int t = t0; t < nt; t += 2) {
;             const bool last = (t == nt - 2);
;             const Src a1 = cA + (size_t)(t + 1) * kstep;
;             const Src a2 = last ? nA : cA + (size_t)(t + 2) * kstep, b2 = last ? nB : cB + (size_t)(t + 2) * kstep;
;             const Src a3 = a2 + kstep, b3 = b2 + kstep;
;             if (last && has_next) H(nxt);
;             if constexpr (SP2) {
;             PG8_TRIP_SP2(PG8_WAIT_V(8));
.LBB0_391:
	s_add_i32 s100, s56, 0xfffc0000
	v_add_u32_e32 v150, 0x10000, v148
	v_add_u32_e32 v151, 0x14000, v148
	ds_read_b128 v[132:135], v150
	ds_read_b128 v[136:139], v150 offset:1024
	ds_read_b128 v[140:143], v150 offset:2048
	ds_read_b128 v[152:155], v150 offset:3072
	ds_read_b128 v[156:159], v151
	ds_read_b128 v[160:163], v151 offset:1024
	ds_read_b128 v[164:167], v151 offset:2048
	ds_read_b128 v[168:171], v151 offset:3072
	s_add_i32 s12, s56, 0xfffc0080
	s_cmp_eq_u32 s29, 12
	s_cselect_b32 s60, s68, s12
	s_cselect_b32 s13, s5, s77
	s_cselect_b32 s12, s4, s76
	s_cselect_b32 s15, s7, s55
	s_cselect_b32 s14, s6, s54
	s_cselect_b32 s58, s69, s57
	s_cselect_b32 s16, s0, s8
	s_cselect_b32 s17, s1, s9
	s_cselect_b32 s18, s2, s10
	s_cselect_b32 s19, s3, s11
	s_or_b32 s59, s60, 0x80
	s_mov_b32 m0, s33
	s_nop 0
	buffer_load_dwordx4 v146, s[8:11], s100 offen lds
	s_mov_b32 m0, s45
	ds_read_b128 v[172:175], v149
	ds_read_b128 v[176:179], v149 offset:1024
	ds_read_b128 v[180:183], v149 offset:2048
	ds_read_b128 v[184:187], v149 offset:3072
	ds_read_b128 v[188:191], v149 offset:4096
	ds_read_b128 v[212:215], v149 offset:5120
	ds_read_b128 v[216:219], v149 offset:6144
	ds_read_b128 v[228:231], v149 offset:7168
	buffer_load_dwordx4 v144, s[8:11], s56 offen lds
	s_mov_b32 m0, s46
	s_nop 0
	buffer_load_dwordx4 v146, s[8:11], s56 offen lds
	s_waitcnt vmcnt(8)
	s_waitcnt lgkmcnt(0)
	s_setprio 1
	s_barrier
	v_mfma_f32_16x16x32_bf16 v[120:123], v[132:135], v[172:175], v[120:123]
	v_mfma_f32_16x16x32_bf16 v[112:115], v[140:143], v[172:175], v[112:115]
	v_mfma_f32_16x16x32_bf16 v[100:103], v[132:135], v[180:183], v[100:103]
	v_mfma_f32_16x16x32_bf16 v[88:91], v[140:143], v[180:183], v[88:91]
	v_mfma_f32_16x16x32_bf16 v[68:71], v[132:135], v[188:191], v[68:71]
	v_mfma_f32_16x16x32_bf16 v[56:59], v[140:143], v[188:191], v[56:59]
	v_mfma_f32_16x16x32_bf16 v[36:39], v[132:135], v[216:219], v[36:39]
	v_mfma_f32_16x16x32_bf16 v[28:31], v[140:143], v[216:219], v[28:31]
	v_mfma_f32_16x16x32_bf16 v[120:123], v[136:139], v[176:179], v[120:123]
	v_mfma_f32_16x16x32_bf16 v[112:115], v[152:155], v[176:179], v[112:115]
	v_mfma_f32_16x16x32_bf16 v[100:103], v[136:139], v[184:187], v[100:103]
	v_mfma_f32_16x16x32_bf16 v[88:91], v[152:155], v[184:187], v[88:91]
	v_mfma_f32_16x16x32_bf16 v[68:71], v[136:139], v[212:215], v[68:71]
	v_mfma_f32_16x16x32_bf16 v[56:59], v[152:155], v[212:215], v[56:59]
	v_mfma_f32_16x16x32_bf16 v[36:39], v[136:139], v[228:231], v[36:39]
	v_mfma_f32_16x16x32_bf16 v[28:31], v[152:155], v[228:231], v[28:31]
	v_mfma_f32_16x16x32_bf16 v[128:131], v[156:159], v[172:175], v[128:131]
	v_mfma_f32_16x16x32_bf16 v[124:127], v[164:167], v[172:175], v[124:127]
	v_mfma_f32_16x16x32_bf16 v[116:119], v[156:159], v[180:183], v[116:119]
	v_mfma_f32_16x16x32_bf16 v[108:111], v[164:167], v[180:183], v[108:111]
	v_mfma_f32_16x16x32_bf16 v[92:95], v[156:159], v[188:191], v[92:95]
	v_mfma_f32_16x16x32_bf16 v[80:83], v[164:167], v[188:191], v[80:83]
	v_mfma_f32_16x16x32_bf16 v[64:67], v[156:159], v[216:219], v[64:67]
	v_mfma_f32_16x16x32_bf16 v[48:51], v[164:167], v[216:219], v[48:51]
	v_mfma_f32_16x16x32_bf16 v[128:131], v[160:163], v[176:179], v[128:131]
	v_mfma_f32_16x16x32_bf16 v[124:127], v[168:171], v[176:179], v[124:127]
	v_mfma_f32_16x16x32_bf16 v[116:119], v[160:163], v[184:187], v[116:119]
	v_mfma_f32_16x16x32_bf16 v[108:111], v[168:171], v[184:187], v[108:111]
	v_mfma_f32_16x16x32_bf16 v[92:95], v[160:163], v[212:215], v[92:95]
	v_mfma_f32_16x16x32_bf16 v[80:83], v[168:171], v[212:215], v[80:83]
	v_mfma_f32_16x16x32_bf16 v[64:67], v[160:163], v[228:231], v[64:67]
	v_mfma_f32_16x16x32_bf16 v[48:51], v[168:171], v[228:231], v[48:51]
	s_barrier
	s_setprio 0
	s_mov_b32 m0, s92
	ds_read_b128 v[172:175], v149 offset:16384
	ds_read_b128 v[176:179], v149 offset:17408
	ds_read_b128 v[180:183], v149 offset:18432
	ds_read_b128 v[184:187], v149 offset:19456
	ds_read_b128 v[188:191], v149 offset:20480
	ds_read_b128 v[212:215], v149 offset:21504
	ds_read_b128 v[216:219], v149 offset:22528
	ds_read_b128 v[228:231], v149 offset:23552
	buffer_load_dwordx4 v145, s[12:15], s58 offen lds
	s_mov_b32 m0, s93
	s_add_i32 s61, s58, 0x40000
	buffer_load_dwordx4 v147, s[12:15], s58 offen lds
	s_mov_b32 m0, s94
	s_nop 0
	buffer_load_dwordx4 v145, s[12:15], s61 offen lds
	s_mov_b32 m0, s95
	s_nop 0
	buffer_load_dwordx4 v147, s[12:15], s61 offen lds
	s_mov_b32 m0, s44
	s_nop 0
	buffer_load_dwordx4 v144, s[16:19], s60 offen lds
	s_waitcnt vmcnt(7)
	s_waitcnt lgkmcnt(0)
	s_setprio 1
	s_barrier
	v_mfma_f32_16x16x32_bf16 v[72:75], v[132:135], v[172:175], v[72:75]
	v_mfma_f32_16x16x32_bf16 v[60:63], v[140:143], v[172:175], v[60:63]
	v_mfma_f32_16x16x32_bf16 v[40:43], v[132:135], v[180:183], v[40:43]
	v_mfma_f32_16x16x32_bf16 v[32:35], v[140:143], v[180:183], v[32:35]
	v_mfma_f32_16x16x32_bf16 v[16:19], v[132:135], v[188:191], v[16:19]
	v_mfma_f32_16x16x32_bf16 v[12:15], v[140:143], v[188:191], v[12:15]
	v_mfma_f32_16x16x32_bf16 v[8:11], v[132:135], v[216:219], v[8:11]
	v_mfma_f32_16x16x32_bf16 v[2:5], v[140:143], v[216:219], v[4:7]
	v_mfma_f32_16x16x32_bf16 v[72:75], v[136:139], v[176:179], v[72:75]
	v_mfma_f32_16x16x32_bf16 v[60:63], v[152:155], v[176:179], v[60:63]
	v_mfma_f32_16x16x32_bf16 v[40:43], v[136:139], v[184:187], v[40:43]
	v_mfma_f32_16x16x32_bf16 v[32:35], v[152:155], v[184:187], v[32:35]
	v_mfma_f32_16x16x32_bf16 v[16:19], v[136:139], v[212:215], v[16:19]
	v_mfma_f32_16x16x32_bf16 v[12:15], v[152:155], v[212:215], v[12:15]
	v_mfma_f32_16x16x32_bf16 v[8:11], v[136:139], v[228:231], v[8:11]
	v_mfma_f32_16x16x32_bf16 v[2:5], v[152:155], v[228:231], v[2:5]
	v_mfma_f32_16x16x32_bf16 v[96:99], v[156:159], v[172:175], v[96:99]
	v_mfma_f32_16x16x32_bf16 v[104:107], v[164:167], v[172:175], v[104:107]
	v_mfma_f32_16x16x32_bf16 v[84:87], v[156:159], v[180:183], v[84:87]
	v_mfma_f32_16x16x32_bf16 v[76:79], v[164:167], v[180:183], v[76:79]
	v_mfma_f32_16x16x32_bf16 v[52:55], v[156:159], v[188:191], v[52:55]
	v_mfma_f32_16x16x32_bf16 v[44:47], v[164:167], v[188:191], v[44:47]
	v_mfma_f32_16x16x32_bf16 v[24:27], v[156:159], v[216:219], v[24:27]
	v_mfma_f32_16x16x32_bf16 v[20:23], v[164:167], v[216:219], v[20:23]
	v_mfma_f32_16x16x32_bf16 v[96:99], v[160:163], v[176:179], v[96:99]
	v_mfma_f32_16x16x32_bf16 v[104:107], v[168:171], v[176:179], v[104:107]
	v_mfma_f32_16x16x32_bf16 v[84:87], v[160:163], v[184:187], v[84:87]
	v_mfma_f32_16x16x32_bf16 v[76:79], v[168:171], v[184:187], v[76:79]
	v_mfma_f32_16x16x32_bf16 v[52:55], v[160:163], v[212:215], v[52:55]
	v_mfma_f32_16x16x32_bf16 v[44:47], v[168:171], v[212:215], v[44:47]
	v_mfma_f32_16x16x32_bf16 v[24:27], v[160:163], v[228:231], v[24:27]
	v_mfma_f32_16x16x32_bf16 v[20:23], v[168:171], v[228:231], v[20:23]
	s_barrier
; #define PG8_STAGE(bufoff, gbase, voff) do { const Src _g = (gbase); _Pragma("unroll") for (int _i = 0; _i < 2; ++_i) \
;         __builtin_amdgcn_raw_ptr_buffer_load_lds(_g.r, (LAS unsigned*)(lds + (bufoff) + ldsw + _i * 8192), 16, (voff)[_i], _g.o, 0, 0); } while (0)
; #define PG8_WAIT_V(n) asm volatile("s_waitcnt vmcnt(" #n ")" ::: "memory")
; template <class Epi, bool ALIGN_EPI, bool SP2, class Hook>
; __device__ __forceinline__ void gemm_phase(LAS unsigned char* lds, const Gemm g, const StaticOrder& S, const Epi& E, Acc& acc, const bool fresh, const Hook& H, const int wave_id) {
;     ...
;         for (int t = t0; t < nt; t += 2) {
;             const bool last = (t == nt - 2);
;             const Src a1 = cA + (size_t)(t + 1) * kstep;
;             const Src a2 = last ? nA : cA + (size_t)(t + 2) * kstep, b2 = last ? nB : cB + (size_t)(t + 2) * kstep;
;             const Src a3 = a2 + kstep, b3 = b2 + kstep;
;             if (last && has_next) H(nxt);
;             if constexpr (SP2) {
;             PG8_TRIP_SP2(PG8_WAIT_V(8));
;             } else {
;             PG8_LDB(B0, 0, 0); PG8_SCHED; PG8_LDA(At, 0, 0); PG8_STAGE(PG8_SA(1, 1), a1 + hstepA, voffA);
;             PG8_WAIT_L(8); PG8_BAR; PG8_WAIT_L(0); PG8_MMA(0, 0, At, B0); PG8_BAR; PG8_SCHED;
;             PG8_LDB(B1, 0, 1); PG8_STAGE(PG8_SB(0, 0), b2, voffB);
;             PG8_BAR; PG8_WAIT_L(0); PG8_MMA(0, 1, At, B1); PG8_BAR;
;             PG8_LDA(At, 0, 1); PG8_STAGE(PG8_SA(0, 0), a2, voffA);
;             PG8_BAR; PG8_WAIT_L(0); PG8_MMA(1, 0, At, B0); PG8_BAR; PG8_SCHED;
;             PG8_STAGE(PG8_SB(0, 1), b2 + hstep, voffB);
;             PG8_WAIT_V(6); PG8_BAR; PG8_MMA(1, 1, At, B1); PG8_BAR;
;             PG8_LDB(B0, 1, 0); PG8_SCHED; PG8_LDA(At, 1, 0); PG8_STAGE(PG8_SA(0, 1), a2 + hstepA, voffA);
;             PG8_WAIT_L(8); PG8_BAR; PG8_WAIT_L(0); PG8_MMA(0, 0, At, B0); PG8_BAR; PG8_SCHED;
;             PG8_LDB(B1, 1, 1); PG8_STAGE(PG8_SB(1, 0), b3, voffB);
;             PG8_BAR; PG8_WAIT_L(0); PG8_MMA(0, 1, At, B1); PG8_BAR;
;             PG8_LDA(At, 1, 1); PG8_STAGE(PG8_SA(1, 0), a3, voffA);
;             PG8_BAR; PG8_WAIT_L(0); PG8_MMA(1, 0, At, B0); PG8_BAR; PG8_SCHED;
;             PG8_STAGE(PG8_SB(1, 1), b3 + hstep, voffB);
;             PG8_WAIT_V(6); PG8_BAR; PG8_MMA(1, 1, At, B1); PG8_BAR;
;             }
;         }
;         if constexpr (ALIGN_EPI) { if (wr == 0) PG8_BAR; }
	s_setprio 0
	s_mov_b32 m0, s36
	s_nop 0
	buffer_load_dwordx4 v146, s[16:19], s60 offen lds
	v_add_u32_e32 v152, 0x18000, v148
	v_add_u32_e32 v153, 0x1c000, v148
	ds_read_b128 v[132:135], v152
	ds_read_b128 v[136:139], v152 offset:1024
	ds_read_b128 v[140:143], v152 offset:2048
	ds_read_b128 v[154:157], v152 offset:3072
	ds_read_b128 v[158:161], v153
	ds_read_b128 v[162:165], v153 offset:1024
	ds_read_b128 v[166:169], v153 offset:2048
	ds_read_b128 v[170:173], v153 offset:3072
	s_add_i32 s60, s60, 0x40000
	s_mov_b32 m0, s37
	ds_read_b128 v[174:177], v149 offset:32768
	ds_read_b128 v[178:181], v149 offset:33792
	ds_read_b128 v[182:185], v149 offset:34816
	ds_read_b128 v[186:189], v149 offset:35840
	ds_read_b128 v[190:193], v149 offset:36864
	ds_read_b128 v[212:215], v149 offset:37888
	ds_read_b128 v[216:219], v149 offset:38912
	ds_read_b128 v[228:231], v149 offset:39936
	buffer_load_dwordx4 v144, s[16:19], s60 offen lds
	s_mov_b32 m0, s38
	s_nop 0
	buffer_load_dwordx4 v146, s[16:19], s60 offen lds
	s_waitcnt vmcnt(8)
	s_waitcnt lgkmcnt(0)
	s_setprio 1
	s_barrier
	v_mfma_f32_16x16x32_bf16 v[120:123], v[132:135], v[174:177], v[120:123]
	v_mfma_f32_16x16x32_bf16 v[112:115], v[140:143], v[174:177], v[112:115]
	v_mfma_f32_16x16x32_bf16 v[100:103], v[132:135], v[182:185], v[100:103]
	v_mfma_f32_16x16x32_bf16 v[88:91], v[140:143], v[182:185], v[88:91]
	v_mfma_f32_16x16x32_bf16 v[68:71], v[132:135], v[190:193], v[68:71]
	v_mfma_f32_16x16x32_bf16 v[56:59], v[140:143], v[190:193], v[56:59]
	v_mfma_f32_16x16x32_bf16 v[36:39], v[132:135], v[216:219], v[36:39]
	v_mfma_f32_16x16x32_bf16 v[28:31], v[140:143], v[216:219], v[28:31]
	v_mfma_f32_16x16x32_bf16 v[120:123], v[136:139], v[178:181], v[120:123]
	v_mfma_f32_16x16x32_bf16 v[112:115], v[154:157], v[178:181], v[112:115]
	v_mfma_f32_16x16x32_bf16 v[100:103], v[136:139], v[186:189], v[100:103]
	v_mfma_f32_16x16x32_bf16 v[88:91], v[154:157], v[186:189], v[88:91]
	v_mfma_f32_16x16x32_bf16 v[68:71], v[136:139], v[212:215], v[68:71]
	v_mfma_f32_16x16x32_bf16 v[56:59], v[154:157], v[212:215], v[56:59]
	v_mfma_f32_16x16x32_bf16 v[36:39], v[136:139], v[228:231], v[36:39]
	v_mfma_f32_16x16x32_bf16 v[28:31], v[154:157], v[228:231], v[28:31]
	v_mfma_f32_16x16x32_bf16 v[128:131], v[158:161], v[174:177], v[128:131]
	v_mfma_f32_16x16x32_bf16 v[124:127], v[166:169], v[174:177], v[124:127]
	v_mfma_f32_16x16x32_bf16 v[116:119], v[158:161], v[182:185], v[116:119]
	v_mfma_f32_16x16x32_bf16 v[108:111], v[166:169], v[182:185], v[108:111]
	v_mfma_f32_16x16x32_bf16 v[92:95], v[158:161], v[190:193], v[92:95]
	v_mfma_f32_16x16x32_bf16 v[80:83], v[166:169], v[190:193], v[80:83]
	v_mfma_f32_16x16x32_bf16 v[64:67], v[158:161], v[216:219], v[64:67]
	v_mfma_f32_16x16x32_bf16 v[48:51], v[166:169], v[216:219], v[48:51]
	v_mfma_f32_16x16x32_bf16 v[128:131], v[162:165], v[178:181], v[128:131]
	v_mfma_f32_16x16x32_bf16 v[124:127], v[170:173], v[178:181], v[124:127]
	v_mfma_f32_16x16x32_bf16 v[116:119], v[162:165], v[186:189], v[116:119]
	v_mfma_f32_16x16x32_bf16 v[108:111], v[170:173], v[186:189], v[108:111]
	v_mfma_f32_16x16x32_bf16 v[92:95], v[162:165], v[212:215], v[92:95]
	v_mfma_f32_16x16x32_bf16 v[80:83], v[170:173], v[212:215], v[80:83]
	v_mfma_f32_16x16x32_bf16 v[64:67], v[162:165], v[228:231], v[64:67]
	v_mfma_f32_16x16x32_bf16 v[48:51], v[170:173], v[228:231], v[48:51]
	s_barrier
	s_setprio 0
	s_mov_b32 m0, s39
	s_or_b32 s60, s58, 0x80
	ds_read_b128 v[174:177], v149 offset:49152
	ds_read_b128 v[178:181], v149 offset:50176
	ds_read_b128 v[182:185], v149 offset:51200
	ds_read_b128 v[186:189], v149 offset:52224
	ds_read_b128 v[190:193], v149 offset:53248
	ds_read_b128 v[212:215], v149 offset:54272
	ds_read_b128 v[216:219], v149 offset:55296
	ds_read_b128 v[228:231], v149 offset:56320
	buffer_load_dwordx4 v145, s[12:15], s60 offen lds
	s_mov_b32 m0, s40
	s_add_i32 s58, s58, 0x40080
	buffer_load_dwordx4 v147, s[12:15], s60 offen lds
	s_mov_b32 m0, s43
	s_nop 0
	buffer_load_dwordx4 v145, s[12:15], s58 offen lds
	s_mov_b32 m0, s42
	s_nop 0
	buffer_load_dwordx4 v147, s[12:15], s58 offen lds
	s_mov_b32 m0, s41
	s_nop 0
	buffer_load_dwordx4 v144, s[16:19], s59 offen lds
	s_waitcnt vmcnt(7)
	s_waitcnt lgkmcnt(0)
	s_setprio 1
	s_barrier
	v_mfma_f32_16x16x32_bf16 v[72:75], v[132:135], v[174:177], v[72:75]
	v_mfma_f32_16x16x32_bf16 v[60:63], v[140:143], v[174:177], v[60:63]
	v_mfma_f32_16x16x32_bf16 v[40:43], v[132:135], v[182:185], v[40:43]
	v_mfma_f32_16x16x32_bf16 v[32:35], v[140:143], v[182:185], v[32:35]
	v_mfma_f32_16x16x32_bf16 v[16:19], v[132:135], v[190:193], v[16:19]
	v_mfma_f32_16x16x32_bf16 v[12:15], v[140:143], v[190:193], v[12:15]
	v_mfma_f32_16x16x32_bf16 v[6:9], v[132:135], v[216:219], v[8:11]
	v_mfma_f32_16x16x32_bf16 v[2:5], v[140:143], v[216:219], v[2:5]
	v_mfma_f32_16x16x32_bf16 v[72:75], v[136:139], v[178:181], v[72:75]
	v_mfma_f32_16x16x32_bf16 v[60:63], v[154:157], v[178:181], v[60:63]
	v_mfma_f32_16x16x32_bf16 v[40:43], v[136:139], v[186:189], v[40:43]
	v_mfma_f32_16x16x32_bf16 v[32:35], v[154:157], v[186:189], v[32:35]
	v_mfma_f32_16x16x32_bf16 v[16:19], v[136:139], v[212:215], v[16:19]
	v_mfma_f32_16x16x32_bf16 v[12:15], v[154:157], v[212:215], v[12:15]
	v_mfma_f32_16x16x32_bf16 v[8:11], v[136:139], v[228:231], v[6:9]
	v_mfma_f32_16x16x32_bf16 v[4:7], v[154:157], v[228:231], v[2:5]
	v_mfma_f32_16x16x32_bf16 v[96:99], v[158:161], v[174:177], v[96:99]
	v_mfma_f32_16x16x32_bf16 v[104:107], v[166:169], v[174:177], v[104:107]
	v_mfma_f32_16x16x32_bf16 v[84:87], v[158:161], v[182:185], v[84:87]
	v_mfma_f32_16x16x32_bf16 v[76:79], v[166:169], v[182:185], v[76:79]
	v_mfma_f32_16x16x32_bf16 v[52:55], v[158:161], v[190:193], v[52:55]
	v_mfma_f32_16x16x32_bf16 v[44:47], v[166:169], v[190:193], v[44:47]
	v_mfma_f32_16x16x32_bf16 v[24:27], v[158:161], v[216:219], v[24:27]
	v_mfma_f32_16x16x32_bf16 v[20:23], v[166:169], v[216:219], v[20:23]
	v_mfma_f32_16x16x32_bf16 v[96:99], v[162:165], v[178:181], v[96:99]
	v_mfma_f32_16x16x32_bf16 v[104:107], v[170:173], v[178:181], v[104:107]
	v_mfma_f32_16x16x32_bf16 v[84:87], v[162:165], v[186:189], v[84:87]
	v_mfma_f32_16x16x32_bf16 v[76:79], v[170:173], v[186:189], v[76:79]
	v_mfma_f32_16x16x32_bf16 v[52:55], v[162:165], v[212:215], v[52:55]
	v_mfma_f32_16x16x32_bf16 v[44:47], v[170:173], v[212:215], v[44:47]
	v_mfma_f32_16x16x32_bf16 v[24:27], v[162:165], v[228:231], v[24:27]
	v_mfma_f32_16x16x32_bf16 v[20:23], v[170:173], v[228:231], v[20:23]
	s_barrier
	s_setprio 0
	s_add_i32 s29, s29, 2
	s_addk_i32 s56, 0x100
	s_addk_i32 s57, 0x100
	s_cmp_gt_u32 s29, 13
	s_cbranch_scc0 .LBB0_391
	s_mov_b32 m0, s33
	s_nop 0
	buffer_load_dwordx4 v146, s[16:19], s59 offen lds
	v_readlane_b32 s8, v251, 45
	v_readlane_b32 s9, v251, 46
	s_and_b64 vcc, exec, s[8:9]
	s_cbranch_vccz .LBB0_394
	s_barrier

; #define PG8_WAIT_V(n) asm volatile("s_waitcnt vmcnt(" #n ")" ::: "memory")
; template <class Epi, bool ALIGN_EPI, bool SP2, class Hook>
; __device__ __forceinline__ void gemm_phase(LAS unsigned char* lds, const Gemm g, const StaticOrder& S, const Epi& E, Acc& acc, const bool fresh, const Hook& H, const int wave_id) {
;     ...
;         for (int t = t0; t < nt; t += 2) {
;             const bool last = (t == nt - 2);
;             const Src a1 = cA + (size_t)(t + 1) * kstep;
;             const Src a2 = last ? nA : cA + (size_t)(t + 2) * kstep, b2 = last ? nB : cB + (size_t)(t + 2) * kstep;
;             const Src a3 = a2 + kstep, b3 = b2 + kstep;
;             if (last && has_next) H(nxt);
;             if constexpr (SP2) {
;             PG8_TRIP_SP2(PG8_WAIT_V(8));
.LBB0_903:
	s_add_i32 s100, s55, 0xfffe0000
	v_add_u32_e32 v70, 0x10000, v216
	v_add_u32_e32 v118, 0x14000, v216
	ds_read_b128 v[34:37], v70
	ds_read_b128 v[46:49], v70 offset:1024
	ds_read_b128 v[58:61], v70 offset:2048
	ds_read_b128 v[70:73], v70 offset:3072
	ds_read_b128 v[82:85], v118
	ds_read_b128 v[94:97], v118 offset:1024
	ds_read_b128 v[106:109], v118 offset:2048
	ds_read_b128 v[118:121], v118 offset:3072
	s_add_i32 s12, s55, 0xfffe0080
	s_cmp_eq_u32 s57, 4
	s_cselect_b32 s60, s53, s12
	s_cselect_b32 s13, s29, s77
	s_cselect_b32 s12, s28, s76
	s_cselect_b32 s15, s31, s35
	s_cselect_b32 s14, s30, s34
	s_cselect_b32 s58, s54, s56
	s_cselect_b32 s16, s2, s8
	s_cselect_b32 s17, s3, s9
	s_cselect_b32 s18, s26, s10
	s_cselect_b32 s19, s27, s11
	s_or_b32 s59, s60, 0x80
	s_mov_b32 m0, s33
	s_nop 0
	buffer_load_dwordx4 v214, s[8:11], s100 offen lds
	s_mov_b32 m0, s45
	ds_read_b128 v[130:133], v217
	ds_read_b128 v[142:145], v217 offset:1024
	ds_read_b128 v[154:157], v217 offset:2048
	ds_read_b128 v[166:169], v217 offset:3072
	ds_read_b128 v[174:177], v217 offset:4096
	ds_read_b128 v[182:185], v217 offset:5120
	ds_read_b128 v[186:189], v217 offset:6144
	ds_read_b128 v[190:193], v217 offset:7168
	buffer_load_dwordx4 v0, s[8:11], s55 offen lds
	s_mov_b32 m0, s46
	s_nop 0
	buffer_load_dwordx4 v214, s[8:11], s55 offen lds
	s_waitcnt vmcnt(8)
	s_waitcnt lgkmcnt(0)
	s_setprio 1
	s_barrier
	v_mfma_f32_16x16x32_bf16 v[178:181], v[34:37], v[130:133], v[178:181]
	v_mfma_f32_16x16x32_bf16 v[170:173], v[58:61], v[130:133], v[170:173]
	v_mfma_f32_16x16x32_bf16 v[150:153], v[34:37], v[154:157], v[150:153]
	v_mfma_f32_16x16x32_bf16 v[146:149], v[58:61], v[154:157], v[146:149]
	v_mfma_f32_16x16x32_bf16 v[126:129], v[34:37], v[174:177], v[126:129]
	v_mfma_f32_16x16x32_bf16 v[122:125], v[58:61], v[174:177], v[122:125]
	v_mfma_f32_16x16x32_bf16 v[102:105], v[34:37], v[186:189], v[102:105]
	v_mfma_f32_16x16x32_bf16 v[98:101], v[58:61], v[186:189], v[98:101]
	v_mfma_f32_16x16x32_bf16 v[178:181], v[46:49], v[142:145], v[178:181]
	v_mfma_f32_16x16x32_bf16 v[170:173], v[70:73], v[142:145], v[170:173]
	v_mfma_f32_16x16x32_bf16 v[150:153], v[46:49], v[166:169], v[150:153]
	v_mfma_f32_16x16x32_bf16 v[146:149], v[70:73], v[166:169], v[146:149]
	v_mfma_f32_16x16x32_bf16 v[126:129], v[46:49], v[182:185], v[126:129]
	v_mfma_f32_16x16x32_bf16 v[122:125], v[70:73], v[182:185], v[122:125]
	v_mfma_f32_16x16x32_bf16 v[102:105], v[46:49], v[190:193], v[102:105]
	v_mfma_f32_16x16x32_bf16 v[98:101], v[70:73], v[190:193], v[98:101]
	v_mfma_f32_16x16x32_bf16 v[162:165], v[82:85], v[130:133], v[162:165]
	v_mfma_f32_16x16x32_bf16 v[138:141], v[82:85], v[154:157], v[138:141]
	v_mfma_f32_16x16x32_bf16 v[134:137], v[106:109], v[154:157], v[134:137]
	v_mfma_f32_16x16x32_bf16 v[114:117], v[82:85], v[174:177], v[114:117]
	v_mfma_f32_16x16x32_bf16 v[110:113], v[106:109], v[174:177], v[110:113]
	v_mfma_f32_16x16x32_bf16 v[90:93], v[82:85], v[186:189], v[90:93]
	v_mfma_f32_16x16x32_bf16 v[86:89], v[106:109], v[186:189], v[86:89]
	v_mfma_f32_16x16x32_bf16 v[162:165], v[94:97], v[142:145], v[162:165]
	v_mfma_f32_16x16x32_bf16 v[130:133], v[106:109], v[130:133], v[158:161]
	v_mfma_f32_16x16x32_bf16 v[138:141], v[94:97], v[166:169], v[138:141]
	v_mfma_f32_16x16x32_bf16 v[134:137], v[118:121], v[166:169], v[134:137]
	v_mfma_f32_16x16x32_bf16 v[114:117], v[94:97], v[182:185], v[114:117]
	v_mfma_f32_16x16x32_bf16 v[110:113], v[118:121], v[182:185], v[110:113]
	v_mfma_f32_16x16x32_bf16 v[90:93], v[94:97], v[190:193], v[90:93]
	v_mfma_f32_16x16x32_bf16 v[86:89], v[118:121], v[190:193], v[86:89]
	v_mfma_f32_16x16x32_bf16 v[130:133], v[118:121], v[142:145], v[130:133]
	s_barrier
	s_setprio 0
	s_mov_b32 m0, s92
	ds_read_b128 v[142:145], v217 offset:16384
	ds_read_b128 v[154:157], v217 offset:17408
	ds_read_b128 v[158:161], v217 offset:18432
	ds_read_b128 v[166:169], v217 offset:19456
	ds_read_b128 v[174:177], v217 offset:20480
	ds_read_b128 v[182:185], v217 offset:21504
	ds_read_b128 v[186:189], v217 offset:22528
	ds_read_b128 v[190:193], v217 offset:23552
	buffer_load_dwordx4 v199, s[12:15], s58 offen lds
	s_mov_b32 m0, s93
	s_add_i32 s61, s58, 0x20000
	buffer_load_dwordx4 v215, s[12:15], s58 offen lds
	s_mov_b32 m0, s94
	s_nop 0
	buffer_load_dwordx4 v199, s[12:15], s61 offen lds
	s_mov_b32 m0, s95
	s_nop 0
	buffer_load_dwordx4 v215, s[12:15], s61 offen lds
	s_mov_b32 m0, s44
	s_nop 0
	buffer_load_dwordx4 v0, s[16:19], s60 offen lds
	s_waitcnt vmcnt(7)
	s_waitcnt lgkmcnt(0)
	s_setprio 1
	s_barrier
	v_mfma_f32_16x16x32_bf16 v[78:81], v[34:37], v[142:145], v[78:81]
	v_mfma_f32_16x16x32_bf16 v[74:77], v[58:61], v[142:145], v[74:77]
	v_mfma_f32_16x16x32_bf16 v[54:57], v[34:37], v[158:161], v[54:57]
	v_mfma_f32_16x16x32_bf16 v[50:53], v[58:61], v[158:161], v[50:53]
	v_mfma_f32_16x16x32_bf16 v[30:33], v[34:37], v[174:177], v[30:33]
	v_mfma_f32_16x16x32_bf16 v[26:29], v[58:61], v[174:177], v[26:29]
	v_mfma_f32_16x16x32_bf16 v[14:17], v[34:37], v[186:189], v[14:17]
	v_mfma_f32_16x16x32_bf16 v[10:13], v[58:61], v[186:189], v[10:13]
	v_mfma_f32_16x16x32_bf16 v[78:81], v[46:49], v[154:157], v[78:81]
	v_mfma_f32_16x16x32_bf16 v[74:77], v[70:73], v[154:157], v[74:77]
	v_mfma_f32_16x16x32_bf16 v[54:57], v[46:49], v[166:169], v[54:57]
	v_mfma_f32_16x16x32_bf16 v[50:53], v[70:73], v[166:169], v[50:53]
	v_mfma_f32_16x16x32_bf16 v[30:33], v[46:49], v[182:185], v[30:33]
	v_mfma_f32_16x16x32_bf16 v[26:29], v[70:73], v[182:185], v[26:29]
	v_mfma_f32_16x16x32_bf16 v[14:17], v[46:49], v[190:193], v[14:17]
	v_mfma_f32_16x16x32_bf16 v[10:13], v[70:73], v[190:193], v[10:13]
	v_mfma_f32_16x16x32_bf16 v[42:45], v[82:85], v[158:161], v[42:45]
	v_mfma_f32_16x16x32_bf16 v[38:41], v[106:109], v[158:161], v[38:41]
	v_mfma_f32_16x16x32_bf16 v[22:25], v[82:85], v[174:177], v[22:25]
	v_mfma_f32_16x16x32_bf16 v[18:21], v[106:109], v[174:177], v[18:21]
	v_mfma_f32_16x16x32_bf16 v[6:9], v[82:85], v[186:189], v[6:9]
	v_mfma_f32_16x16x32_bf16 v[2:5], v[106:109], v[186:189], v[2:5]
	v_mfma_f32_16x16x32_bf16 v[34:37], v[82:85], v[142:145], v[66:69]
	v_mfma_f32_16x16x32_bf16 v[46:49], v[106:109], v[142:145], v[62:65]
	v_mfma_f32_16x16x32_bf16 v[42:45], v[94:97], v[166:169], v[42:45]
	v_mfma_f32_16x16x32_bf16 v[38:41], v[118:121], v[166:169], v[38:41]
	v_mfma_f32_16x16x32_bf16 v[22:25], v[94:97], v[182:185], v[22:25]
	v_mfma_f32_16x16x32_bf16 v[18:21], v[118:121], v[182:185], v[18:21]
	v_mfma_f32_16x16x32_bf16 v[6:9], v[94:97], v[190:193], v[6:9]
	v_mfma_f32_16x16x32_bf16 v[2:5], v[118:121], v[190:193], v[2:5]
	v_mfma_f32_16x16x32_bf16 v[34:37], v[94:97], v[154:157], v[34:37]
	v_mfma_f32_16x16x32_bf16 v[46:49], v[118:121], v[154:157], v[46:49]
	s_barrier
; #define PG8_STAGE(bufoff, gbase, voff) do { const Src _g = (gbase); _Pragma("unroll") for (int _i = 0; _i < 2; ++_i) \
;         __builtin_amdgcn_raw_ptr_buffer_load_lds(_g.r, (LAS unsigned*)(lds + (bufoff) + ldsw + _i * 8192), 16, (voff)[_i], _g.o, 0, 0); } while (0)
; #define PG8_WAIT_V(n) asm volatile("s_waitcnt vmcnt(" #n ")" ::: "memory")
; template <class Epi, bool ALIGN_EPI, bool SP2, class Hook>
; __device__ __forceinline__ void gemm_phase(LAS unsigned char* lds, const Gemm g, const StaticOrder& S, const Epi& E, Acc& acc, const bool fresh, const Hook& H, const int wave_id) {
;     ...
;         for (int t = t0; t < nt; t += 2) {
;             const bool last = (t == nt - 2);
;             const Src a1 = cA + (size_t)(t + 1) * kstep;
;             const Src a2 = last ? nA : cA + (size_t)(t + 2) * kstep, b2 = last ? nB : cB + (size_t)(t + 2) * kstep;
;             const Src a3 = a2 + kstep, b3 = b2 + kstep;
;             if (last && has_next) H(nxt);
;             if constexpr (SP2) {
;             PG8_TRIP_SP2(PG8_WAIT_V(8));
;             } else {
;             PG8_LDB(B0, 0, 0); PG8_SCHED; PG8_LDA(At, 0, 0); PG8_STAGE(PG8_SA(1, 1), a1 + hstepA, voffA);
;             PG8_WAIT_L(8); PG8_BAR; PG8_WAIT_L(0); PG8_MMA(0, 0, At, B0); PG8_BAR; PG8_SCHED;
;             PG8_LDB(B1, 0, 1); PG8_STAGE(PG8_SB(0, 0), b2, voffB);
;             PG8_BAR; PG8_WAIT_L(0); PG8_MMA(0, 1, At, B1); PG8_BAR;
;             PG8_LDA(At, 0, 1); PG8_STAGE(PG8_SA(0, 0), a2, voffA);
;             PG8_BAR; PG8_WAIT_L(0); PG8_MMA(1, 0, At, B0); PG8_BAR; PG8_SCHED;
;             PG8_STAGE(PG8_SB(0, 1), b2 + hstep, voffB);
;             PG8_WAIT_V(6); PG8_BAR; PG8_MMA(1, 1, At, B1); PG8_BAR;
;             PG8_LDB(B0, 1, 0); PG8_SCHED; PG8_LDA(At, 1, 0); PG8_STAGE(PG8_SA(0, 1), a2 + hstepA, voffA);
;             PG8_WAIT_L(8); PG8_BAR; PG8_WAIT_L(0); PG8_MMA(0, 0, At, B0); PG8_BAR; PG8_SCHED;
;             PG8_LDB(B1, 1, 1); PG8_STAGE(PG8_SB(1, 0), b3, voffB);
;             PG8_BAR; PG8_WAIT_L(0); PG8_MMA(0, 1, At, B1); PG8_BAR;
;             PG8_LDA(At, 1, 1); PG8_STAGE(PG8_SA(1, 0), a3, voffA);
;             PG8_BAR; PG8_WAIT_L(0); PG8_MMA(1, 0, At, B0); PG8_BAR; PG8_SCHED;
;             PG8_STAGE(PG8_SB(1, 1), b3 + hstep, voffB);
;             PG8_WAIT_V(6); PG8_BAR; PG8_MMA(1, 1, At, B1); PG8_BAR;
;             }
;         }
;         if constexpr (ALIGN_EPI) { if (wr == 0) PG8_BAR; }
	s_setprio 0
	s_mov_b32 m0, s36
	s_nop 0
	buffer_load_dwordx4 v214, s[16:19], s60 offen lds
	v_add_u32_e32 v70, 0x18000, v216
	v_add_u32_e32 v118, 0x1c000, v216
	ds_read_b128 v[58:61], v70
	ds_read_b128 v[62:65], v70 offset:1024
	ds_read_b128 v[66:69], v70 offset:2048
	ds_read_b128 v[70:73], v70 offset:3072
	ds_read_b128 v[82:85], v118
	ds_read_b128 v[94:97], v118 offset:1024
	ds_read_b128 v[106:109], v118 offset:2048
	ds_read_b128 v[118:121], v118 offset:3072
	s_add_i32 s60, s60, 0x20000
	s_mov_b32 m0, s37
	ds_read_b128 v[142:145], v217 offset:32768
	ds_read_b128 v[154:157], v217 offset:33792
	ds_read_b128 v[166:169], v217 offset:34816
	ds_read_b128 v[174:177], v217 offset:35840
	ds_read_b128 v[182:185], v217 offset:36864
	ds_read_b128 v[186:189], v217 offset:37888
	ds_read_b128 v[190:193], v217 offset:38912
	ds_read_b128 v[194:197], v217 offset:39936
	buffer_load_dwordx4 v0, s[16:19], s60 offen lds
	s_mov_b32 m0, s38
	s_nop 0
	buffer_load_dwordx4 v214, s[16:19], s60 offen lds
	s_waitcnt vmcnt(8)
	s_waitcnt lgkmcnt(0)
	s_setprio 1
	s_barrier
	v_mfma_f32_16x16x32_bf16 v[158:161], v[58:61], v[142:145], v[178:181]
	v_mfma_f32_16x16x32_bf16 v[178:181], v[62:65], v[154:157], v[158:161]
	v_mfma_f32_16x16x32_bf16 v[158:161], v[66:69], v[142:145], v[170:173]
	v_mfma_f32_16x16x32_bf16 v[150:153], v[58:61], v[166:169], v[150:153]
	v_mfma_f32_16x16x32_bf16 v[146:149], v[66:69], v[166:169], v[146:149]
	v_mfma_f32_16x16x32_bf16 v[126:129], v[58:61], v[182:185], v[126:129]
	v_mfma_f32_16x16x32_bf16 v[122:125], v[66:69], v[182:185], v[122:125]
	v_mfma_f32_16x16x32_bf16 v[102:105], v[58:61], v[190:193], v[102:105]
	v_mfma_f32_16x16x32_bf16 v[98:101], v[66:69], v[190:193], v[98:101]
	v_mfma_f32_16x16x32_bf16 v[170:173], v[70:73], v[154:157], v[158:161]
	v_mfma_f32_16x16x32_bf16 v[150:153], v[62:65], v[174:177], v[150:153]
	v_mfma_f32_16x16x32_bf16 v[146:149], v[70:73], v[174:177], v[146:149]
	v_mfma_f32_16x16x32_bf16 v[126:129], v[62:65], v[186:189], v[126:129]
	v_mfma_f32_16x16x32_bf16 v[122:125], v[70:73], v[186:189], v[122:125]
	v_mfma_f32_16x16x32_bf16 v[102:105], v[62:65], v[194:197], v[102:105]
	v_mfma_f32_16x16x32_bf16 v[98:101], v[70:73], v[194:197], v[98:101]
	v_mfma_f32_16x16x32_bf16 v[158:161], v[82:85], v[142:145], v[162:165]
	v_mfma_f32_16x16x32_bf16 v[130:133], v[106:109], v[142:145], v[130:133]
	v_mfma_f32_16x16x32_bf16 v[162:165], v[94:97], v[154:157], v[158:161]
	v_mfma_f32_16x16x32_bf16 v[158:161], v[118:121], v[154:157], v[130:133]
	v_mfma_f32_16x16x32_bf16 v[130:133], v[82:85], v[166:169], v[138:141]
	v_mfma_f32_16x16x32_bf16 v[138:141], v[94:97], v[174:177], v[130:133]
	v_mfma_f32_16x16x32_bf16 v[130:133], v[106:109], v[166:169], v[134:137]
	v_mfma_f32_16x16x32_bf16 v[114:117], v[82:85], v[182:185], v[114:117]
	v_mfma_f32_16x16x32_bf16 v[110:113], v[106:109], v[182:185], v[110:113]
	v_mfma_f32_16x16x32_bf16 v[90:93], v[82:85], v[190:193], v[90:93]
	v_mfma_f32_16x16x32_bf16 v[86:89], v[106:109], v[190:193], v[86:89]
	v_mfma_f32_16x16x32_bf16 v[134:137], v[118:121], v[174:177], v[130:133]
	v_mfma_f32_16x16x32_bf16 v[114:117], v[94:97], v[186:189], v[114:117]
	v_mfma_f32_16x16x32_bf16 v[110:113], v[118:121], v[186:189], v[110:113]
	v_mfma_f32_16x16x32_bf16 v[90:93], v[94:97], v[194:197], v[90:93]
	v_mfma_f32_16x16x32_bf16 v[86:89], v[118:121], v[194:197], v[86:89]
	s_barrier
	s_setprio 0
	s_mov_b32 m0, s39
	s_or_b32 s60, s58, 0x80
	ds_read_b128 v[130:133], v217 offset:49152
	ds_read_b128 v[142:145], v217 offset:50176
	ds_read_b128 v[154:157], v217 offset:51200
	ds_read_b128 v[166:169], v217 offset:52224
	ds_read_b128 v[174:177], v217 offset:53248
	ds_read_b128 v[182:185], v217 offset:54272
	ds_read_b128 v[186:189], v217 offset:55296
	ds_read_b128 v[190:193], v217 offset:56320
	buffer_load_dwordx4 v199, s[12:15], s60 offen lds
	s_mov_b32 m0, s40
	s_add_i32 s58, s58, 0x20080
	buffer_load_dwordx4 v215, s[12:15], s60 offen lds
	s_mov_b32 m0, s43
	s_nop 0
	buffer_load_dwordx4 v199, s[12:15], s58 offen lds
	s_mov_b32 m0, s42
	s_nop 0
	buffer_load_dwordx4 v215, s[12:15], s58 offen lds
	s_mov_b32 m0, s41
	s_nop 0
	buffer_load_dwordx4 v0, s[16:19], s59 offen lds
	s_waitcnt vmcnt(7)
	s_waitcnt lgkmcnt(0)
	s_setprio 1
	s_barrier
	v_mfma_f32_16x16x32_bf16 v[78:81], v[58:61], v[130:133], v[78:81]
	v_mfma_f32_16x16x32_bf16 v[74:77], v[66:69], v[130:133], v[74:77]
	v_mfma_f32_16x16x32_bf16 v[54:57], v[58:61], v[154:157], v[54:57]
	v_mfma_f32_16x16x32_bf16 v[50:53], v[66:69], v[154:157], v[50:53]
	v_mfma_f32_16x16x32_bf16 v[30:33], v[58:61], v[174:177], v[30:33]
	v_mfma_f32_16x16x32_bf16 v[26:29], v[66:69], v[174:177], v[26:29]
	v_mfma_f32_16x16x32_bf16 v[14:17], v[58:61], v[186:189], v[14:17]
	v_mfma_f32_16x16x32_bf16 v[10:13], v[66:69], v[186:189], v[10:13]
	v_mfma_f32_16x16x32_bf16 v[78:81], v[62:65], v[142:145], v[78:81]
	v_mfma_f32_16x16x32_bf16 v[74:77], v[70:73], v[142:145], v[74:77]
	v_mfma_f32_16x16x32_bf16 v[54:57], v[62:65], v[166:169], v[54:57]
	v_mfma_f32_16x16x32_bf16 v[50:53], v[70:73], v[166:169], v[50:53]
	v_mfma_f32_16x16x32_bf16 v[30:33], v[62:65], v[182:185], v[30:33]
	v_mfma_f32_16x16x32_bf16 v[26:29], v[70:73], v[182:185], v[26:29]
	v_mfma_f32_16x16x32_bf16 v[14:17], v[62:65], v[190:193], v[14:17]
	v_mfma_f32_16x16x32_bf16 v[10:13], v[70:73], v[190:193], v[10:13]
	v_mfma_f32_16x16x32_bf16 v[34:37], v[82:85], v[130:133], v[34:37]
	v_mfma_f32_16x16x32_bf16 v[66:69], v[94:97], v[142:145], v[34:37]
	v_mfma_f32_16x16x32_bf16 v[34:37], v[106:109], v[130:133], v[46:49]
	v_mfma_f32_16x16x32_bf16 v[62:65], v[118:121], v[142:145], v[34:37]
	v_mfma_f32_16x16x32_bf16 v[34:37], v[82:85], v[154:157], v[42:45]
	v_mfma_f32_16x16x32_bf16 v[42:45], v[94:97], v[166:169], v[34:37]
	v_mfma_f32_16x16x32_bf16 v[34:37], v[106:109], v[154:157], v[38:41]
	v_mfma_f32_16x16x32_bf16 v[22:25], v[82:85], v[174:177], v[22:25]
	v_mfma_f32_16x16x32_bf16 v[18:21], v[106:109], v[174:177], v[18:21]
	v_mfma_f32_16x16x32_bf16 v[6:9], v[82:85], v[186:189], v[6:9]
	v_mfma_f32_16x16x32_bf16 v[2:5], v[106:109], v[186:189], v[2:5]
	v_mfma_f32_16x16x32_bf16 v[38:41], v[118:121], v[166:169], v[34:37]
	v_mfma_f32_16x16x32_bf16 v[22:25], v[94:97], v[182:185], v[22:25]
	v_mfma_f32_16x16x32_bf16 v[18:21], v[118:121], v[182:185], v[18:21]
	v_mfma_f32_16x16x32_bf16 v[6:9], v[94:97], v[190:193], v[6:9]
	v_mfma_f32_16x16x32_bf16 v[2:5], v[118:121], v[190:193], v[2:5]
	s_barrier
	s_setprio 0
	s_add_i32 s57, s57, 2
	s_addk_i32 s55, 0x100
	s_addk_i32 s56, 0x100
	s_cmp_gt_u32 s57, 5
	s_cbranch_scc0 .LBB0_903
	s_mov_b32 m0, s33
	s_nop 0
	buffer_load_dwordx4 v214, s[16:19], s59 offen lds
	v_readlane_b32 s8, v251, 45
	v_readlane_b32 s9, v251, 46
	s_and_b64 vcc, exec, s[8:9]
	s_cbranch_vccz .LBB0_906
	s_barrier

; #define PG8_WAIT_V(n) asm volatile("s_waitcnt vmcnt(" #n ")" ::: "memory")
; template <class Epi, bool ALIGN_EPI, bool SP2, class Hook>
; __device__ __forceinline__ void gemm_phase(LAS unsigned char* lds, const Gemm g, const StaticOrder& S, const Epi& E, Acc& acc, const bool fresh, const Hook& H, const int wave_id) {
;     ...
;         for (int t = t0; t < nt; t += 2) {
;             const bool last = (t == nt - 2);
;             const Src a1 = cA + (size_t)(t + 1) * kstep;
;             const Src a2 = last ? nA : cA + (size_t)(t + 2) * kstep, b2 = last ? nB : cB + (size_t)(t + 2) * kstep;
;             const Src a3 = a2 + kstep, b3 = b2 + kstep;
;             if (last && has_next) H(nxt);
;             if constexpr (SP2) {
;             PG8_TRIP_SP2(PG8_WAIT_V(8));
.LBB0_1235:
	s_add_i32 s100, s2, 0xfffc0000
	v_add_u32_e32 v142, 0x10000, v161
	v_add_u32_e32 v163, 0x14000, v161
	ds_read_b128 v[130:133], v142
	ds_read_b128 v[134:137], v142 offset:1024
	ds_read_b128 v[138:141], v142 offset:2048
	ds_read_b128 v[142:145], v142 offset:3072
	ds_read_b128 v[146:149], v163
	ds_read_b128 v[150:153], v163 offset:1024
	ds_read_b128 v[154:157], v163 offset:2048
	ds_read_b128 v[164:167], v163 offset:3072
	s_add_i32 s16, s2, 0xfffc0080
	s_cmp_eq_u32 s59, 12
	s_cselect_b32 s62, s55, s16
	s_cselect_b32 s17, s31, s9
	s_cselect_b32 s16, s30, s8
	s_cselect_b32 s19, s35, s51
	s_cselect_b32 s18, s34, s50
	s_cselect_b32 s60, s56, s3
	s_cselect_b32 s20, s26, s12
	s_cselect_b32 s21, s27, s13
	s_cselect_b32 s22, s28, s14
	s_cselect_b32 s23, s29, s15
	s_or_b32 s61, s62, 0x80
	s_mov_b32 m0, s33
	s_nop 0
	buffer_load_dwordx4 v159, s[12:15], s100 offen lds
	s_mov_b32 m0, s45
	ds_read_b128 v[168:171], v162
	ds_read_b128 v[172:175], v162 offset:1024
	ds_read_b128 v[176:179], v162 offset:2048
	ds_read_b128 v[180:183], v162 offset:3072
	ds_read_b128 v[184:187], v162 offset:4096
	ds_read_b128 v[188:191], v162 offset:5120
	ds_read_b128 v[192:195], v162 offset:6144
	ds_read_b128 v[200:203], v162 offset:7168
	buffer_load_dwordx4 v0, s[12:15], s2 offen lds
	s_mov_b32 m0, s46
	s_nop 0
	buffer_load_dwordx4 v159, s[12:15], s2 offen lds
	s_waitcnt vmcnt(8)
	s_waitcnt lgkmcnt(0)
	s_setprio 1
	s_barrier
	v_mfma_f32_16x16x32_bf16 v[126:129], v[130:133], v[168:171], v[126:129]
	v_mfma_f32_16x16x32_bf16 v[122:125], v[138:141], v[168:171], v[122:125]
	v_mfma_f32_16x16x32_bf16 v[110:113], v[130:133], v[176:179], v[110:113]
	v_mfma_f32_16x16x32_bf16 v[106:109], v[138:141], v[176:179], v[106:109]
	v_mfma_f32_16x16x32_bf16 v[94:97], v[130:133], v[184:187], v[94:97]
	v_mfma_f32_16x16x32_bf16 v[90:93], v[138:141], v[184:187], v[90:93]
	v_mfma_f32_16x16x32_bf16 v[78:81], v[130:133], v[192:195], v[78:81]
	v_mfma_f32_16x16x32_bf16 v[74:77], v[138:141], v[192:195], v[74:77]
	v_mfma_f32_16x16x32_bf16 v[126:129], v[134:137], v[172:175], v[126:129]
	v_mfma_f32_16x16x32_bf16 v[122:125], v[142:145], v[172:175], v[122:125]
	v_mfma_f32_16x16x32_bf16 v[110:113], v[134:137], v[180:183], v[110:113]
	v_mfma_f32_16x16x32_bf16 v[106:109], v[142:145], v[180:183], v[106:109]
	v_mfma_f32_16x16x32_bf16 v[94:97], v[134:137], v[188:191], v[94:97]
	v_mfma_f32_16x16x32_bf16 v[90:93], v[142:145], v[188:191], v[90:93]
	v_mfma_f32_16x16x32_bf16 v[78:81], v[134:137], v[200:203], v[78:81]
	v_mfma_f32_16x16x32_bf16 v[74:77], v[142:145], v[200:203], v[74:77]
	v_mfma_f32_16x16x32_bf16 v[118:121], v[146:149], v[168:171], v[118:121]
	v_mfma_f32_16x16x32_bf16 v[114:117], v[154:157], v[168:171], v[114:117]
	v_mfma_f32_16x16x32_bf16 v[102:105], v[146:149], v[176:179], v[102:105]
	v_mfma_f32_16x16x32_bf16 v[98:101], v[154:157], v[176:179], v[98:101]
	v_mfma_f32_16x16x32_bf16 v[86:89], v[146:149], v[184:187], v[86:89]
	v_mfma_f32_16x16x32_bf16 v[82:85], v[154:157], v[184:187], v[82:85]
	v_mfma_f32_16x16x32_bf16 v[70:73], v[146:149], v[192:195], v[70:73]
	v_mfma_f32_16x16x32_bf16 v[66:69], v[154:157], v[192:195], v[66:69]
	v_mfma_f32_16x16x32_bf16 v[118:121], v[150:153], v[172:175], v[118:121]
	v_mfma_f32_16x16x32_bf16 v[114:117], v[164:167], v[172:175], v[114:117]
	v_mfma_f32_16x16x32_bf16 v[102:105], v[150:153], v[180:183], v[102:105]
	v_mfma_f32_16x16x32_bf16 v[98:101], v[164:167], v[180:183], v[98:101]
	v_mfma_f32_16x16x32_bf16 v[86:89], v[150:153], v[188:191], v[86:89]
	v_mfma_f32_16x16x32_bf16 v[82:85], v[164:167], v[188:191], v[82:85]
	v_mfma_f32_16x16x32_bf16 v[70:73], v[150:153], v[200:203], v[70:73]
	v_mfma_f32_16x16x32_bf16 v[66:69], v[164:167], v[200:203], v[66:69]
	s_barrier
	s_setprio 0
	s_mov_b32 m0, s92
	ds_read_b128 v[168:171], v162 offset:16384
	ds_read_b128 v[172:175], v162 offset:17408
	ds_read_b128 v[176:179], v162 offset:18432
	ds_read_b128 v[180:183], v162 offset:19456
	ds_read_b128 v[184:187], v162 offset:20480
	ds_read_b128 v[188:191], v162 offset:21504
	ds_read_b128 v[192:195], v162 offset:22528
	ds_read_b128 v[200:203], v162 offset:23552
	buffer_load_dwordx4 v158, s[16:19], s60 offen lds
	s_mov_b32 m0, s93
	s_add_i32 s63, s60, 0x40000
	buffer_load_dwordx4 v160, s[16:19], s60 offen lds
	s_mov_b32 m0, s94
	s_nop 0
	buffer_load_dwordx4 v158, s[16:19], s63 offen lds
	s_mov_b32 m0, s95
	s_nop 0
	buffer_load_dwordx4 v160, s[16:19], s63 offen lds
	s_mov_b32 m0, s44
	s_nop 0
	buffer_load_dwordx4 v0, s[20:23], s62 offen lds
	s_waitcnt vmcnt(7)
	s_waitcnt lgkmcnt(0)
	s_setprio 1
	s_barrier
	v_mfma_f32_16x16x32_bf16 v[62:65], v[130:133], v[168:171], v[62:65]
	v_mfma_f32_16x16x32_bf16 v[58:61], v[138:141], v[168:171], v[58:61]
	v_mfma_f32_16x16x32_bf16 v[46:49], v[130:133], v[176:179], v[46:49]
	v_mfma_f32_16x16x32_bf16 v[42:45], v[138:141], v[176:179], v[42:45]
	v_mfma_f32_16x16x32_bf16 v[30:33], v[130:133], v[184:187], v[30:33]
	v_mfma_f32_16x16x32_bf16 v[26:29], v[138:141], v[184:187], v[26:29]
	v_mfma_f32_16x16x32_bf16 v[14:17], v[130:133], v[192:195], v[14:17]
	v_mfma_f32_16x16x32_bf16 v[10:13], v[138:141], v[192:195], v[10:13]
	v_mfma_f32_16x16x32_bf16 v[62:65], v[134:137], v[172:175], v[62:65]
	v_mfma_f32_16x16x32_bf16 v[58:61], v[142:145], v[172:175], v[58:61]
	v_mfma_f32_16x16x32_bf16 v[46:49], v[134:137], v[180:183], v[46:49]
	v_mfma_f32_16x16x32_bf16 v[42:45], v[142:145], v[180:183], v[42:45]
	v_mfma_f32_16x16x32_bf16 v[30:33], v[134:137], v[188:191], v[30:33]
	v_mfma_f32_16x16x32_bf16 v[26:29], v[142:145], v[188:191], v[26:29]
	v_mfma_f32_16x16x32_bf16 v[14:17], v[134:137], v[200:203], v[14:17]
	v_mfma_f32_16x16x32_bf16 v[10:13], v[142:145], v[200:203], v[10:13]
	v_mfma_f32_16x16x32_bf16 v[54:57], v[146:149], v[168:171], v[54:57]
	v_mfma_f32_16x16x32_bf16 v[50:53], v[154:157], v[168:171], v[50:53]
	v_mfma_f32_16x16x32_bf16 v[38:41], v[146:149], v[176:179], v[38:41]
	v_mfma_f32_16x16x32_bf16 v[34:37], v[154:157], v[176:179], v[34:37]
	v_mfma_f32_16x16x32_bf16 v[22:25], v[146:149], v[184:187], v[22:25]
	v_mfma_f32_16x16x32_bf16 v[18:21], v[154:157], v[184:187], v[18:21]
	v_mfma_f32_16x16x32_bf16 v[6:9], v[146:149], v[192:195], v[6:9]
	v_mfma_f32_16x16x32_bf16 v[2:5], v[154:157], v[192:195], v[2:5]
	v_mfma_f32_16x16x32_bf16 v[54:57], v[150:153], v[172:175], v[54:57]
	v_mfma_f32_16x16x32_bf16 v[50:53], v[164:167], v[172:175], v[50:53]
	v_mfma_f32_16x16x32_bf16 v[38:41], v[150:153], v[180:183], v[38:41]
	v_mfma_f32_16x16x32_bf16 v[34:37], v[164:167], v[180:183], v[34:37]
	v_mfma_f32_16x16x32_bf16 v[22:25], v[150:153], v[188:191], v[22:25]
	v_mfma_f32_16x16x32_bf16 v[18:21], v[164:167], v[188:191], v[18:21]
	v_mfma_f32_16x16x32_bf16 v[6:9], v[150:153], v[200:203], v[6:9]
	v_mfma_f32_16x16x32_bf16 v[2:5], v[164:167], v[200:203], v[2:5]
	s_barrier
; #define PG8_STAGE(bufoff, gbase, voff) do { const Src _g = (gbase); _Pragma("unroll") for (int _i = 0; _i < 2; ++_i) \
;         __builtin_amdgcn_raw_ptr_buffer_load_lds(_g.r, (LAS unsigned*)(lds + (bufoff) + ldsw + _i * 8192), 16, (voff)[_i], _g.o, 0, 0); } while (0)
; #define PG8_WAIT_V(n) asm volatile("s_waitcnt vmcnt(" #n ")" ::: "memory")
; template <class Epi, bool ALIGN_EPI, bool SP2, class Hook>
; __device__ __forceinline__ void gemm_phase(LAS unsigned char* lds, const Gemm g, const StaticOrder& S, const Epi& E, Acc& acc, const bool fresh, const Hook& H, const int wave_id) {
;     ...
;         for (int t = t0; t < nt; t += 2) {
;             const bool last = (t == nt - 2);
;             const Src a1 = cA + (size_t)(t + 1) * kstep;
;             const Src a2 = last ? nA : cA + (size_t)(t + 2) * kstep, b2 = last ? nB : cB + (size_t)(t + 2) * kstep;
;             const Src a3 = a2 + kstep, b3 = b2 + kstep;
;             if (last && has_next) H(nxt);
;             if constexpr (SP2) {
;             PG8_TRIP_SP2(PG8_WAIT_V(8));
;             } else {
;             PG8_LDB(B0, 0, 0); PG8_SCHED; PG8_LDA(At, 0, 0); PG8_STAGE(PG8_SA(1, 1), a1 + hstepA, voffA);
;             PG8_WAIT_L(8); PG8_BAR; PG8_WAIT_L(0); PG8_MMA(0, 0, At, B0); PG8_BAR; PG8_SCHED;
;             PG8_LDB(B1, 0, 1); PG8_STAGE(PG8_SB(0, 0), b2, voffB);
;             PG8_BAR; PG8_WAIT_L(0); PG8_MMA(0, 1, At, B1); PG8_BAR;
;             PG8_LDA(At, 0, 1); PG8_STAGE(PG8_SA(0, 0), a2, voffA);
;             PG8_BAR; PG8_WAIT_L(0); PG8_MMA(1, 0, At, B0); PG8_BAR; PG8_SCHED;
;             PG8_STAGE(PG8_SB(0, 1), b2 + hstep, voffB);
;             PG8_WAIT_V(6); PG8_BAR; PG8_MMA(1, 1, At, B1); PG8_BAR;
;             PG8_LDB(B0, 1, 0); PG8_SCHED; PG8_LDA(At, 1, 0); PG8_STAGE(PG8_SA(0, 1), a2 + hstepA, voffA);
;             PG8_WAIT_L(8); PG8_BAR; PG8_WAIT_L(0); PG8_MMA(0, 0, At, B0); PG8_BAR; PG8_SCHED;
;             PG8_LDB(B1, 1, 1); PG8_STAGE(PG8_SB(1, 0), b3, voffB);
;             PG8_BAR; PG8_WAIT_L(0); PG8_MMA(0, 1, At, B1); PG8_BAR;
;             PG8_LDA(At, 1, 1); PG8_STAGE(PG8_SA(1, 0), a3, voffA);
;             PG8_BAR; PG8_WAIT_L(0); PG8_MMA(1, 0, At, B0); PG8_BAR; PG8_SCHED;
;             PG8_STAGE(PG8_SB(1, 1), b3 + hstep, voffB);
;             PG8_WAIT_V(6); PG8_BAR; PG8_MMA(1, 1, At, B1); PG8_BAR;
;             }
;         }
;         if constexpr (ALIGN_EPI) { if (wr == 0) PG8_BAR; }
	s_setprio 0
	s_mov_b32 m0, s36
	s_nop 0
	buffer_load_dwordx4 v159, s[20:23], s62 offen lds
	v_add_u32_e32 v142, 0x18000, v161
	v_add_u32_e32 v163, 0x1c000, v161
	ds_read_b128 v[130:133], v142
	ds_read_b128 v[134:137], v142 offset:1024
	ds_read_b128 v[138:141], v142 offset:2048
	ds_read_b128 v[142:145], v142 offset:3072
	ds_read_b128 v[146:149], v163
	ds_read_b128 v[150:153], v163 offset:1024
	ds_read_b128 v[154:157], v163 offset:2048
	ds_read_b128 v[164:167], v163 offset:3072
	s_add_i32 s62, s62, 0x40000
	s_mov_b32 m0, s37
	ds_read_b128 v[168:171], v162 offset:32768
	ds_read_b128 v[172:175], v162 offset:33792
	ds_read_b128 v[176:179], v162 offset:34816
	ds_read_b128 v[180:183], v162 offset:35840
	ds_read_b128 v[184:187], v162 offset:36864
	ds_read_b128 v[188:191], v162 offset:37888
	ds_read_b128 v[192:195], v162 offset:38912
	ds_read_b128 v[200:203], v162 offset:39936
	buffer_load_dwordx4 v0, s[20:23], s62 offen lds
	s_mov_b32 m0, s38
	s_nop 0
	buffer_load_dwordx4 v159, s[20:23], s62 offen lds
	s_waitcnt vmcnt(8)
	s_waitcnt lgkmcnt(0)
	s_setprio 1
	s_barrier
	v_mfma_f32_16x16x32_bf16 v[126:129], v[130:133], v[168:171], v[126:129]
	v_mfma_f32_16x16x32_bf16 v[122:125], v[138:141], v[168:171], v[122:125]
	v_mfma_f32_16x16x32_bf16 v[110:113], v[130:133], v[176:179], v[110:113]
	v_mfma_f32_16x16x32_bf16 v[106:109], v[138:141], v[176:179], v[106:109]
	v_mfma_f32_16x16x32_bf16 v[94:97], v[130:133], v[184:187], v[94:97]
	v_mfma_f32_16x16x32_bf16 v[90:93], v[138:141], v[184:187], v[90:93]
	v_mfma_f32_16x16x32_bf16 v[78:81], v[130:133], v[192:195], v[78:81]
	v_mfma_f32_16x16x32_bf16 v[74:77], v[138:141], v[192:195], v[74:77]
	v_mfma_f32_16x16x32_bf16 v[126:129], v[134:137], v[172:175], v[126:129]
	v_mfma_f32_16x16x32_bf16 v[122:125], v[142:145], v[172:175], v[122:125]
	v_mfma_f32_16x16x32_bf16 v[110:113], v[134:137], v[180:183], v[110:113]
	v_mfma_f32_16x16x32_bf16 v[106:109], v[142:145], v[180:183], v[106:109]
	v_mfma_f32_16x16x32_bf16 v[94:97], v[134:137], v[188:191], v[94:97]
	v_mfma_f32_16x16x32_bf16 v[90:93], v[142:145], v[188:191], v[90:93]
	v_mfma_f32_16x16x32_bf16 v[78:81], v[134:137], v[200:203], v[78:81]
	v_mfma_f32_16x16x32_bf16 v[74:77], v[142:145], v[200:203], v[74:77]
	v_mfma_f32_16x16x32_bf16 v[118:121], v[146:149], v[168:171], v[118:121]
	v_mfma_f32_16x16x32_bf16 v[114:117], v[154:157], v[168:171], v[114:117]
	v_mfma_f32_16x16x32_bf16 v[102:105], v[146:149], v[176:179], v[102:105]
	v_mfma_f32_16x16x32_bf16 v[98:101], v[154:157], v[176:179], v[98:101]
	v_mfma_f32_16x16x32_bf16 v[86:89], v[146:149], v[184:187], v[86:89]
	v_mfma_f32_16x16x32_bf16 v[82:85], v[154:157], v[184:187], v[82:85]
	v_mfma_f32_16x16x32_bf16 v[70:73], v[146:149], v[192:195], v[70:73]
	v_mfma_f32_16x16x32_bf16 v[66:69], v[154:157], v[192:195], v[66:69]
	v_mfma_f32_16x16x32_bf16 v[118:121], v[150:153], v[172:175], v[118:121]
	v_mfma_f32_16x16x32_bf16 v[114:117], v[164:167], v[172:175], v[114:117]
	v_mfma_f32_16x16x32_bf16 v[102:105], v[150:153], v[180:183], v[102:105]
	v_mfma_f32_16x16x32_bf16 v[98:101], v[164:167], v[180:183], v[98:101]
	v_mfma_f32_16x16x32_bf16 v[86:89], v[150:153], v[188:191], v[86:89]
	v_mfma_f32_16x16x32_bf16 v[82:85], v[164:167], v[188:191], v[82:85]
	v_mfma_f32_16x16x32_bf16 v[70:73], v[150:153], v[200:203], v[70:73]
	v_mfma_f32_16x16x32_bf16 v[66:69], v[164:167], v[200:203], v[66:69]
	s_barrier
	s_setprio 0
	s_mov_b32 m0, s39
	s_or_b32 s62, s60, 0x80
	ds_read_b128 v[168:171], v162 offset:49152
	ds_read_b128 v[172:175], v162 offset:50176
	ds_read_b128 v[176:179], v162 offset:51200
	ds_read_b128 v[180:183], v162 offset:52224
	ds_read_b128 v[184:187], v162 offset:53248
	ds_read_b128 v[188:191], v162 offset:54272
	ds_read_b128 v[192:195], v162 offset:55296
	ds_read_b128 v[200:203], v162 offset:56320
	buffer_load_dwordx4 v158, s[16:19], s62 offen lds
	s_mov_b32 m0, s40
	s_add_i32 s60, s60, 0x40080
	buffer_load_dwordx4 v160, s[16:19], s62 offen lds
	s_mov_b32 m0, s43
	s_nop 0
	buffer_load_dwordx4 v158, s[16:19], s60 offen lds
	s_mov_b32 m0, s42
	s_nop 0
	buffer_load_dwordx4 v160, s[16:19], s60 offen lds
	s_mov_b32 m0, s41
	s_nop 0
	buffer_load_dwordx4 v0, s[20:23], s61 offen lds
	s_waitcnt vmcnt(7)
	s_waitcnt lgkmcnt(0)
	s_setprio 1
	s_barrier
	v_mfma_f32_16x16x32_bf16 v[62:65], v[130:133], v[168:171], v[62:65]
	v_mfma_f32_16x16x32_bf16 v[58:61], v[138:141], v[168:171], v[58:61]
	v_mfma_f32_16x16x32_bf16 v[46:49], v[130:133], v[176:179], v[46:49]
	v_mfma_f32_16x16x32_bf16 v[42:45], v[138:141], v[176:179], v[42:45]
	v_mfma_f32_16x16x32_bf16 v[30:33], v[130:133], v[184:187], v[30:33]
	v_mfma_f32_16x16x32_bf16 v[26:29], v[138:141], v[184:187], v[26:29]
	v_mfma_f32_16x16x32_bf16 v[14:17], v[130:133], v[192:195], v[14:17]
	v_mfma_f32_16x16x32_bf16 v[10:13], v[138:141], v[192:195], v[10:13]
	v_mfma_f32_16x16x32_bf16 v[62:65], v[134:137], v[172:175], v[62:65]
	v_mfma_f32_16x16x32_bf16 v[58:61], v[142:145], v[172:175], v[58:61]
	v_mfma_f32_16x16x32_bf16 v[46:49], v[134:137], v[180:183], v[46:49]
	v_mfma_f32_16x16x32_bf16 v[42:45], v[142:145], v[180:183], v[42:45]
	v_mfma_f32_16x16x32_bf16 v[30:33], v[134:137], v[188:191], v[30:33]
	v_mfma_f32_16x16x32_bf16 v[26:29], v[142:145], v[188:191], v[26:29]
	v_mfma_f32_16x16x32_bf16 v[14:17], v[134:137], v[200:203], v[14:17]
	v_mfma_f32_16x16x32_bf16 v[10:13], v[142:145], v[200:203], v[10:13]
	v_mfma_f32_16x16x32_bf16 v[54:57], v[146:149], v[168:171], v[54:57]
	v_mfma_f32_16x16x32_bf16 v[50:53], v[154:157], v[168:171], v[50:53]
	v_mfma_f32_16x16x32_bf16 v[38:41], v[146:149], v[176:179], v[38:41]
	v_mfma_f32_16x16x32_bf16 v[34:37], v[154:157], v[176:179], v[34:37]
	v_mfma_f32_16x16x32_bf16 v[22:25], v[146:149], v[184:187], v[22:25]
	v_mfma_f32_16x16x32_bf16 v[18:21], v[154:157], v[184:187], v[18:21]
	v_mfma_f32_16x16x32_bf16 v[6:9], v[146:149], v[192:195], v[6:9]
	v_mfma_f32_16x16x32_bf16 v[2:5], v[154:157], v[192:195], v[2:5]
	v_mfma_f32_16x16x32_bf16 v[54:57], v[150:153], v[172:175], v[54:57]
	v_mfma_f32_16x16x32_bf16 v[50:53], v[164:167], v[172:175], v[50:53]
	v_mfma_f32_16x16x32_bf16 v[38:41], v[150:153], v[180:183], v[38:41]
	v_mfma_f32_16x16x32_bf16 v[34:37], v[164:167], v[180:183], v[34:37]
	v_mfma_f32_16x16x32_bf16 v[22:25], v[150:153], v[188:191], v[22:25]
	v_mfma_f32_16x16x32_bf16 v[18:21], v[164:167], v[188:191], v[18:21]
	v_mfma_f32_16x16x32_bf16 v[6:9], v[150:153], v[200:203], v[6:9]
	v_mfma_f32_16x16x32_bf16 v[2:5], v[164:167], v[200:203], v[2:5]
	s_barrier
	s_setprio 0
	s_add_i32 s59, s59, 2
	s_addk_i32 s2, 0x100
	s_addk_i32 s3, 0x100
	s_cmp_gt_u32 s59, 13
	s_cbranch_scc0 .LBB0_1235
	s_mov_b32 m0, s33
	s_nop 0
	buffer_load_dwordx4 v159, s[20:23], s61 offen lds
	v_readlane_b32 s2, v251, 45
	v_readlane_b32 s3, v251, 46
	s_and_b64 vcc, exec, s[2:3]
	s_cbranch_vccz .LBB0_1238
	s_barrier

; #define PG8_WAIT_V(n) asm volatile("s_waitcnt vmcnt(" #n ")" ::: "memory")
; template <class Epi, bool ALIGN_EPI, bool SP2, class Hook>
; __device__ __forceinline__ void gemm_phase(LAS unsigned char* lds, const Gemm g, const StaticOrder& S, const Epi& E, Acc& acc, const bool fresh, const Hook& H, const int wave_id) {
;     ...
;         if constexpr (SP2 && Epi::NSTORE > 0) {
;             const Src a1 = cA + kstep, a2 = cA + 2 * kstep, b2 = cB + 2 * kstep, a3 = a2 + kstep, b3 = b2 + kstep;
;             if constexpr (Epi::NSTORE == 16) PG8_TRIP_SP2(PG8_WAIT_V(24)); else PG8_TRIP_SP2(PG8_WAIT_V(16));
;             t0 = 2;
.LBB0_1452:
	ds_read_b128 v[2:5], v138
	ds_read_b128 v[6:9], v138 offset:1024
	ds_read_b128 v[10:13], v138 offset:2048
	ds_read_b128 v[14:17], v138 offset:3072
	ds_read_b128 v[18:21], v139
	ds_read_b128 v[22:25], v139 offset:1024
	ds_read_b128 v[26:29], v139 offset:2048
	ds_read_b128 v[30:33], v139 offset:3072
	s_or_b32 s3, s50, 0x100
	s_or_b32 s2, s50, 0x180
	s_or_b32 s12, s51, 0x100
	s_or_b32 s13, s50, 0x40080
	s_mov_b32 m0, s45
	ds_read_b128 v[34:37], v137
	ds_read_b128 v[38:41], v137 offset:1024
	ds_read_b128 v[42:45], v137 offset:2048
	ds_read_b128 v[46:49], v137 offset:3072
	ds_read_b128 v[50:53], v137 offset:4096
	ds_read_b128 v[54:57], v137 offset:5120
	ds_read_b128 v[58:61], v137 offset:6144
	ds_read_b128 v[62:65], v137 offset:7168
	buffer_load_dwordx4 v132, s[4:7], s13 offen lds
	s_mov_b32 m0, s46
	s_nop 0
	buffer_load_dwordx4 v134, s[4:7], s13 offen lds
	s_waitcnt vmcnt(16)
	s_waitcnt lgkmcnt(0)
	s_setprio 1
	s_barrier
	v_mfma_f32_16x16x32_bf16 v[90:93], v[2:5], v[58:61], 0
	v_mfma_f32_16x16x32_bf16 v[66:69], v[2:5], v[34:37], 0
	v_mfma_f32_16x16x32_bf16 v[70:73], v[10:13], v[34:37], 0
	v_mfma_f32_16x16x32_bf16 v[74:77], v[2:5], v[42:45], 0
	v_mfma_f32_16x16x32_bf16 v[78:81], v[10:13], v[42:45], 0
	v_mfma_f32_16x16x32_bf16 v[82:85], v[2:5], v[50:53], 0
	v_mfma_f32_16x16x32_bf16 v[86:89], v[10:13], v[50:53], 0
	v_mfma_f32_16x16x32_bf16 v[96:99], v[6:9], v[62:65], v[90:93]
	v_mfma_f32_16x16x32_bf16 v[90:93], v[10:13], v[58:61], 0
	v_mfma_f32_16x16x32_bf16 v[66:69], v[6:9], v[38:41], v[66:69]
	v_mfma_f32_16x16x32_bf16 v[70:73], v[14:17], v[38:41], v[70:73]
	v_mfma_f32_16x16x32_bf16 v[74:77], v[6:9], v[46:49], v[74:77]
	v_mfma_f32_16x16x32_bf16 v[78:81], v[14:17], v[46:49], v[78:81]
	v_mfma_f32_16x16x32_bf16 v[82:85], v[6:9], v[54:57], v[82:85]
	v_mfma_f32_16x16x32_bf16 v[86:89], v[14:17], v[54:57], v[86:89]
	v_mfma_f32_16x16x32_bf16 v[104:107], v[14:17], v[62:65], v[90:93]
	v_mfma_f32_16x16x32_bf16 v[90:93], v[18:21], v[34:37], 0
	v_mfma_f32_16x16x32_bf16 v[34:37], v[26:29], v[34:37], 0
	v_mfma_f32_16x16x32_bf16 v[112:115], v[22:25], v[38:41], v[90:93]
	v_mfma_f32_16x16x32_bf16 v[34:37], v[30:33], v[38:41], v[34:37]
	v_mfma_f32_16x16x32_bf16 v[38:41], v[18:21], v[42:45], 0
	v_mfma_f32_16x16x32_bf16 v[42:45], v[26:29], v[42:45], 0
	v_mfma_f32_16x16x32_bf16 v[38:41], v[22:25], v[46:49], v[38:41]
	v_mfma_f32_16x16x32_bf16 v[42:45], v[30:33], v[46:49], v[42:45]
	v_mfma_f32_16x16x32_bf16 v[46:49], v[18:21], v[50:53], 0
	v_mfma_f32_16x16x32_bf16 v[50:53], v[26:29], v[50:53], 0
	v_mfma_f32_16x16x32_bf16 v[46:49], v[22:25], v[54:57], v[46:49]
	v_mfma_f32_16x16x32_bf16 v[50:53], v[30:33], v[54:57], v[50:53]
	v_mfma_f32_16x16x32_bf16 v[54:57], v[18:21], v[58:61], 0
	v_mfma_f32_16x16x32_bf16 v[58:61], v[26:29], v[58:61], 0
	v_mfma_f32_16x16x32_bf16 v[54:57], v[22:25], v[62:65], v[54:57]
	v_mfma_f32_16x16x32_bf16 v[58:61], v[30:33], v[62:65], v[58:61]
	s_barrier
	s_setprio 0
	s_mov_b32 m0, s92
	ds_read_b128 v[62:65], v137 offset:16384
	ds_read_b128 v[90:93], v137 offset:17408
	ds_read_b128 v[100:103], v137 offset:18432
	ds_read_b128 v[108:111], v137 offset:19456
	ds_read_b128 v[116:119], v137 offset:20480
	ds_read_b128 v[120:123], v137 offset:21504
	ds_read_b128 v[124:127], v137 offset:22528
	ds_read_b128 v[128:131], v137 offset:23552
	buffer_load_dwordx4 v133, s[8:11], s12 offen lds
	s_mov_b32 m0, s93
	s_nop 0
	buffer_load_dwordx4 v135, s[8:11], s12 offen lds
	s_or_b32 s12, s51, 0x40100
	s_mov_b32 m0, s94
	s_nop 0
	buffer_load_dwordx4 v133, s[8:11], s12 offen lds
	s_mov_b32 m0, s95
	s_nop 0
	buffer_load_dwordx4 v135, s[8:11], s12 offen lds
	s_mov_b32 m0, s44
	s_nop 0
	buffer_load_dwordx4 v132, s[4:7], s3 offen lds
	s_waitcnt vmcnt(15)
	s_waitcnt lgkmcnt(0)
	s_setprio 1
	s_barrier
	v_mfma_f32_16x16x32_bf16 v[142:145], v[2:5], v[62:65], 0
	v_mfma_f32_16x16x32_bf16 v[150:153], v[2:5], v[100:103], 0
	v_mfma_f32_16x16x32_bf16 v[158:161], v[2:5], v[116:119], 0
	v_mfma_f32_16x16x32_bf16 v[2:5], v[2:5], v[124:127], 0
	v_mfma_f32_16x16x32_bf16 v[142:145], v[6:9], v[90:93], v[142:145]
	v_mfma_f32_16x16x32_bf16 v[150:153], v[6:9], v[108:111], v[150:153]
	v_mfma_f32_16x16x32_bf16 v[158:161], v[6:9], v[120:123], v[158:161]
	v_mfma_f32_16x16x32_bf16 v[2:5], v[6:9], v[128:131], v[2:5]
	v_mfma_f32_16x16x32_bf16 v[6:9], v[10:13], v[124:127], 0
	v_mfma_f32_16x16x32_bf16 v[146:149], v[10:13], v[62:65], 0
	v_mfma_f32_16x16x32_bf16 v[154:157], v[10:13], v[100:103], 0
	v_mfma_f32_16x16x32_bf16 v[162:165], v[10:13], v[116:119], 0
	v_mfma_f32_16x16x32_bf16 v[6:9], v[14:17], v[128:131], v[6:9]
	v_mfma_f32_16x16x32_bf16 v[146:149], v[14:17], v[90:93], v[146:149]
	v_mfma_f32_16x16x32_bf16 v[154:157], v[14:17], v[108:111], v[154:157]
	v_mfma_f32_16x16x32_bf16 v[162:165], v[14:17], v[120:123], v[162:165]
	v_mfma_f32_16x16x32_bf16 v[10:13], v[18:21], v[62:65], 0
	v_mfma_f32_16x16x32_bf16 v[166:169], v[22:25], v[90:93], v[10:13]
	v_mfma_f32_16x16x32_bf16 v[10:13], v[26:29], v[62:65], 0
	v_mfma_f32_16x16x32_bf16 v[170:173], v[30:33], v[90:93], v[10:13]
	v_mfma_f32_16x16x32_bf16 v[10:13], v[18:21], v[100:103], 0
	v_mfma_f32_16x16x32_bf16 v[174:177], v[22:25], v[108:111], v[10:13]
	v_mfma_f32_16x16x32_bf16 v[10:13], v[26:29], v[100:103], 0
	v_mfma_f32_16x16x32_bf16 v[178:181], v[30:33], v[108:111], v[10:13]
	v_mfma_f32_16x16x32_bf16 v[10:13], v[18:21], v[116:119], 0
	v_mfma_f32_16x16x32_bf16 v[182:185], v[22:25], v[120:123], v[10:13]
	v_mfma_f32_16x16x32_bf16 v[10:13], v[26:29], v[116:119], 0
	v_mfma_f32_16x16x32_bf16 v[186:189], v[30:33], v[120:123], v[10:13]
	v_mfma_f32_16x16x32_bf16 v[10:13], v[18:21], v[124:127], 0
	v_mfma_f32_16x16x32_bf16 v[16:19], v[22:25], v[128:131], v[10:13]
	v_mfma_f32_16x16x32_bf16 v[10:13], v[26:29], v[124:127], 0
	v_mfma_f32_16x16x32_bf16 v[190:193], v[30:33], v[128:131], v[10:13]
	s_barrier
; #define PG8_WAIT_V(n) asm volatile("s_waitcnt vmcnt(" #n ")" ::: "memory")
; template <class Epi, bool ALIGN_EPI, bool SP2, class Hook>
; __device__ __forceinline__ void gemm_phase(LAS unsigned char* lds, const Gemm g, const StaticOrder& S, const Epi& E, Acc& acc, const bool fresh, const Hook& H, const int wave_id) {
;     ...
;         if constexpr (SP2 && Epi::NSTORE > 0) {
;             const Src a1 = cA + kstep, a2 = cA + 2 * kstep, b2 = cB + 2 * kstep, a3 = a2 + kstep, b3 = b2 + kstep;
;             if constexpr (Epi::NSTORE == 16) PG8_TRIP_SP2(PG8_WAIT_V(24)); else PG8_TRIP_SP2(PG8_WAIT_V(16));
;             t0 = 2;
	s_setprio 0
	s_mov_b32 m0, s36
	s_nop 0
	buffer_load_dwordx4 v134, s[4:7], s3 offen lds
	s_nop 4
	ds_read_b128 v[10:13], v140
	ds_read_b128 v[24:27], v140 offset:1024
	ds_read_b128 v[194:197], v140 offset:2048
	ds_read_b128 v[200:203], v140 offset:3072
	ds_read_b128 v[204:207], v141
	ds_read_b128 v[208:211], v141 offset:1024
	ds_read_b128 v[212:215], v141 offset:2048
	ds_read_b128 v[138:141], v141 offset:3072
	s_or_b32 s3, s50, 0x40100
	s_mov_b32 m0, s37
	ds_read_b128 v[20:23], v137 offset:32768
	ds_read_b128 v[28:31], v137 offset:33792
	ds_read_b128 v[216:219], v137 offset:34816
	ds_read_b128 v[220:223], v137 offset:35840
	ds_read_b128 v[228:231], v137 offset:36864
	ds_read_b128 v[232:235], v137 offset:37888
	ds_read_b128 v[236:239], v137 offset:38912
	ds_read_b128 v[240:243], v137 offset:39936
	buffer_load_dwordx4 v132, s[4:7], s3 offen lds
	s_mov_b32 m0, s38
	s_nop 0
	buffer_load_dwordx4 v134, s[4:7], s3 offen lds
	s_waitcnt vmcnt(8)
	s_waitcnt lgkmcnt(0)
	s_setprio 1
	s_barrier
	v_mfma_f32_16x16x32_bf16 v[62:65], v[10:13], v[20:23], v[66:69]
	v_mfma_f32_16x16x32_bf16 v[124:127], v[24:27], v[28:31], v[62:65]
	v_mfma_f32_16x16x32_bf16 v[62:65], v[194:197], v[20:23], v[70:73]
	v_mfma_f32_16x16x32_bf16 v[116:119], v[200:203], v[28:31], v[62:65]
	v_mfma_f32_16x16x32_bf16 v[62:65], v[10:13], v[216:219], v[74:77]
	v_mfma_f32_16x16x32_bf16 v[108:111], v[24:27], v[220:223], v[62:65]
	v_mfma_f32_16x16x32_bf16 v[62:65], v[194:197], v[216:219], v[78:81]
	v_mfma_f32_16x16x32_bf16 v[100:103], v[200:203], v[220:223], v[62:65]
	v_mfma_f32_16x16x32_bf16 v[62:65], v[10:13], v[228:231], v[82:85]
	v_mfma_f32_16x16x32_bf16 v[92:95], v[24:27], v[232:235], v[62:65]
	v_mfma_f32_16x16x32_bf16 v[62:65], v[194:197], v[228:231], v[86:89]
	v_mfma_f32_16x16x32_bf16 v[84:87], v[200:203], v[232:235], v[62:65]
	v_mfma_f32_16x16x32_bf16 v[62:65], v[10:13], v[236:239], v[96:99]
	v_mfma_f32_16x16x32_bf16 v[76:79], v[24:27], v[240:243], v[62:65]
	v_mfma_f32_16x16x32_bf16 v[62:65], v[194:197], v[236:239], v[104:107]
	v_mfma_f32_16x16x32_bf16 v[64:67], v[200:203], v[240:243], v[62:65]
	v_mfma_f32_16x16x32_bf16 v[68:71], v[204:207], v[20:23], v[112:115]
	v_mfma_f32_16x16x32_bf16 v[20:23], v[212:215], v[20:23], v[34:37]
	v_mfma_f32_16x16x32_bf16 v[120:123], v[138:141], v[28:31], v[20:23]
	v_mfma_f32_16x16x32_bf16 v[20:23], v[204:207], v[216:219], v[38:41]
	v_mfma_f32_16x16x32_bf16 v[112:115], v[208:211], v[220:223], v[20:23]
	v_mfma_f32_16x16x32_bf16 v[20:23], v[212:215], v[216:219], v[42:45]
	v_mfma_f32_16x16x32_bf16 v[104:107], v[138:141], v[220:223], v[20:23]
	v_mfma_f32_16x16x32_bf16 v[20:23], v[204:207], v[228:231], v[46:49]
	v_mfma_f32_16x16x32_bf16 v[96:99], v[208:211], v[232:235], v[20:23]
	v_mfma_f32_16x16x32_bf16 v[20:23], v[212:215], v[228:231], v[50:53]
	v_mfma_f32_16x16x32_bf16 v[88:91], v[138:141], v[232:235], v[20:23]
	v_mfma_f32_16x16x32_bf16 v[20:23], v[204:207], v[236:239], v[54:57]
	v_mfma_f32_16x16x32_bf16 v[80:83], v[208:211], v[240:243], v[20:23]
	v_mfma_f32_16x16x32_bf16 v[20:23], v[212:215], v[236:239], v[58:61]
	v_mfma_f32_16x16x32_bf16 v[128:131], v[208:211], v[28:31], v[68:71]
	v_mfma_f32_16x16x32_bf16 v[68:71], v[138:141], v[240:243], v[20:23]
	s_barrier
	s_setprio 0
	s_mov_b32 m0, s39
	s_or_b32 s3, s51, 0x180
	ds_read_b128 v[32:35], v137 offset:49152
	ds_read_b128 v[40:43], v137 offset:50176
	ds_read_b128 v[216:219], v137 offset:51200
	ds_read_b128 v[220:223], v137 offset:52224
	ds_read_b128 v[228:231], v137 offset:53248
	ds_read_b128 v[232:235], v137 offset:54272
	ds_read_b128 v[236:239], v137 offset:55296
	ds_read_b128 v[240:243], v137 offset:56320
	buffer_load_dwordx4 v133, s[8:11], s3 offen lds
	s_mov_b32 m0, s40
	s_nop 0
	buffer_load_dwordx4 v135, s[8:11], s3 offen lds
	s_or_b32 s3, s51, 0x40180
	s_mov_b32 m0, s43
	s_nop 0
	buffer_load_dwordx4 v133, s[8:11], s3 offen lds
	s_mov_b32 m0, s42
	s_nop 0
	buffer_load_dwordx4 v135, s[8:11], s3 offen lds
	s_mov_b32 m0, s41
	s_nop 0
	buffer_load_dwordx4 v132, s[4:7], s2 offen lds
	s_waitcnt vmcnt(7)
	s_waitcnt lgkmcnt(0)
	s_setprio 1
	s_barrier
	v_mfma_f32_16x16x32_bf16 v[20:23], v[10:13], v[32:35], v[142:145]
	v_mfma_f32_16x16x32_bf16 v[60:63], v[24:27], v[40:43], v[20:23]
	v_mfma_f32_16x16x32_bf16 v[20:23], v[194:197], v[32:35], v[146:149]
	v_mfma_f32_16x16x32_bf16 v[52:55], v[200:203], v[40:43], v[20:23]
	v_mfma_f32_16x16x32_bf16 v[20:23], v[10:13], v[216:219], v[150:153]
	v_mfma_f32_16x16x32_bf16 v[44:47], v[24:27], v[220:223], v[20:23]
	v_mfma_f32_16x16x32_bf16 v[20:23], v[194:197], v[216:219], v[154:157]
	v_mfma_f32_16x16x32_bf16 v[36:39], v[200:203], v[220:223], v[20:23]
	v_mfma_f32_16x16x32_bf16 v[20:23], v[10:13], v[228:231], v[158:161]
	v_mfma_f32_16x16x32_bf16 v[2:5], v[10:13], v[236:239], v[2:5]
	v_mfma_f32_16x16x32_bf16 v[28:31], v[24:27], v[232:235], v[20:23]
	v_mfma_f32_16x16x32_bf16 v[20:23], v[194:197], v[228:231], v[162:165]
	v_mfma_f32_16x16x32_bf16 v[12:15], v[24:27], v[240:243], v[2:5]
	v_mfma_f32_16x16x32_bf16 v[2:5], v[194:197], v[236:239], v[6:9]
	v_mfma_f32_16x16x32_bf16 v[20:23], v[200:203], v[232:235], v[20:23]
	v_mfma_f32_16x16x32_bf16 v[4:7], v[200:203], v[240:243], v[2:5]
	v_mfma_f32_16x16x32_bf16 v[8:11], v[204:207], v[32:35], v[166:169]
	v_mfma_f32_16x16x32_bf16 v[72:75], v[208:211], v[40:43], v[8:11]
	v_mfma_f32_16x16x32_bf16 v[8:11], v[212:215], v[32:35], v[170:173]
	v_mfma_f32_16x16x32_bf16 v[56:59], v[138:141], v[40:43], v[8:11]
	v_mfma_f32_16x16x32_bf16 v[8:11], v[204:207], v[216:219], v[174:177]
	v_mfma_f32_16x16x32_bf16 v[48:51], v[208:211], v[220:223], v[8:11]
	v_mfma_f32_16x16x32_bf16 v[8:11], v[212:215], v[216:219], v[178:181]
	v_mfma_f32_16x16x32_bf16 v[40:43], v[138:141], v[220:223], v[8:11]
	v_mfma_f32_16x16x32_bf16 v[8:11], v[204:207], v[228:231], v[182:185]
	v_mfma_f32_16x16x32_bf16 v[32:35], v[208:211], v[232:235], v[8:11]
	v_mfma_f32_16x16x32_bf16 v[8:11], v[212:215], v[228:231], v[186:189]
	v_mfma_f32_16x16x32_bf16 v[24:27], v[138:141], v[232:235], v[8:11]
	v_mfma_f32_16x16x32_bf16 v[8:11], v[204:207], v[236:239], v[16:19]
	v_mfma_f32_16x16x32_bf16 v[16:19], v[208:211], v[240:243], v[8:11]
	v_mfma_f32_16x16x32_bf16 v[8:11], v[212:215], v[236:239], v[190:193]
	v_mfma_f32_16x16x32_bf16 v[8:11], v[138:141], v[240:243], v[8:11]
	s_barrier
	s_setprio 0
	s_mov_b64 s[2:3], 0
	v_mov_b64_e32 v[234:235], v[226:227]
	v_mov_b32_e32 v226, v0
	v_mov_b64_e32 v[236:237], v[198:199]
	v_mov_b32_e32 v198, v225

; #define PG8_WAIT_V(n) asm volatile("s_waitcnt vmcnt(" #n ")" ::: "memory")
; template <class Epi, bool ALIGN_EPI, bool SP2, class Hook>
; __device__ __forceinline__ void gemm_phase(LAS unsigned char* lds, const Gemm g, const StaticOrder& S, const Epi& E, Acc& acc, const bool fresh, const Hook& H, const int wave_id) {
;     ...
;         for (int t = t0; t < nt; t += 2) {
;             const bool last = (t == nt - 2);
;             const Src a1 = cA + (size_t)(t + 1) * kstep;
;             const Src a2 = last ? nA : cA + (size_t)(t + 2) * kstep, b2 = last ? nB : cB + (size_t)(t + 2) * kstep;
;             const Src a3 = a2 + kstep, b3 = b2 + kstep;
;             if (last && has_next) H(nxt);
;             if constexpr (SP2) {
;             PG8_TRIP_SP2(PG8_WAIT_V(8));
.LBB0_1461:
	s_add_i32 s100, s55, 0xfffc0000
	v_add_u32_e32 v138, 0x10000, v136
	v_add_u32_e32 v139, 0x14000, v136
	ds_read_b128 v[140:143], v138
	ds_read_b128 v[144:147], v138 offset:1024
	ds_read_b128 v[148:151], v138 offset:2048
	ds_read_b128 v[152:155], v138 offset:3072
	ds_read_b128 v[156:159], v139
	ds_read_b128 v[160:163], v139 offset:1024
	ds_read_b128 v[164:167], v139 offset:2048
	ds_read_b128 v[168:171], v139 offset:3072
	s_add_i32 s16, s55, 0xfffc0080
	s_cmp_eq_u32 s54, 12
	s_cselect_b32 s59, s50, s16
	s_cselect_b32 s17, s9, s77
	s_cselect_b32 s16, s8, s76
	s_cselect_b32 s19, s11, s29
	s_cselect_b32 s18, s10, s28
	s_cselect_b32 s57, s51, s56
	s_cselect_b32 s20, s4, s12
	s_cselect_b32 s21, s5, s13
	s_cselect_b32 s22, s6, s14
	s_cselect_b32 s23, s7, s15
	s_or_b32 s58, s59, 0x80
	s_mov_b32 m0, s33
	s_nop 0
	buffer_load_dwordx4 v134, s[12:15], s100 offen lds
	s_mov_b32 m0, s45
	ds_read_b128 v[172:175], v137
	ds_read_b128 v[176:179], v137 offset:1024
	ds_read_b128 v[180:183], v137 offset:2048
	ds_read_b128 v[184:187], v137 offset:3072
	ds_read_b128 v[188:191], v137 offset:4096
	ds_read_b128 v[192:195], v137 offset:5120
	ds_read_b128 v[200:203], v137 offset:6144
	ds_read_b128 v[204:207], v137 offset:7168
	buffer_load_dwordx4 v132, s[12:15], s55 offen lds
	s_mov_b32 m0, s46
	s_nop 0
	buffer_load_dwordx4 v134, s[12:15], s55 offen lds
	s_waitcnt vmcnt(8)
	s_waitcnt lgkmcnt(0)
	s_setprio 1
	s_barrier
	v_mfma_f32_16x16x32_bf16 v[124:127], v[140:143], v[172:175], v[124:127]
	v_mfma_f32_16x16x32_bf16 v[116:119], v[148:151], v[172:175], v[116:119]
	v_mfma_f32_16x16x32_bf16 v[108:111], v[140:143], v[180:183], v[108:111]
	v_mfma_f32_16x16x32_bf16 v[100:103], v[148:151], v[180:183], v[100:103]
	v_mfma_f32_16x16x32_bf16 v[92:95], v[140:143], v[188:191], v[92:95]
	v_mfma_f32_16x16x32_bf16 v[84:87], v[148:151], v[188:191], v[84:87]
	v_mfma_f32_16x16x32_bf16 v[76:79], v[140:143], v[200:203], v[76:79]
	v_mfma_f32_16x16x32_bf16 v[64:67], v[148:151], v[200:203], v[64:67]
	v_mfma_f32_16x16x32_bf16 v[124:127], v[144:147], v[176:179], v[124:127]
	v_mfma_f32_16x16x32_bf16 v[116:119], v[152:155], v[176:179], v[116:119]
	v_mfma_f32_16x16x32_bf16 v[108:111], v[144:147], v[184:187], v[108:111]
	v_mfma_f32_16x16x32_bf16 v[100:103], v[152:155], v[184:187], v[100:103]
	v_mfma_f32_16x16x32_bf16 v[92:95], v[144:147], v[192:195], v[92:95]
	v_mfma_f32_16x16x32_bf16 v[84:87], v[152:155], v[192:195], v[84:87]
	v_mfma_f32_16x16x32_bf16 v[76:79], v[144:147], v[204:207], v[76:79]
	v_mfma_f32_16x16x32_bf16 v[64:67], v[152:155], v[204:207], v[64:67]
	v_mfma_f32_16x16x32_bf16 v[128:131], v[156:159], v[172:175], v[128:131]
	v_mfma_f32_16x16x32_bf16 v[120:123], v[164:167], v[172:175], v[120:123]
	v_mfma_f32_16x16x32_bf16 v[112:115], v[156:159], v[180:183], v[112:115]
	v_mfma_f32_16x16x32_bf16 v[104:107], v[164:167], v[180:183], v[104:107]
	v_mfma_f32_16x16x32_bf16 v[96:99], v[156:159], v[188:191], v[96:99]
	v_mfma_f32_16x16x32_bf16 v[88:91], v[164:167], v[188:191], v[88:91]
	v_mfma_f32_16x16x32_bf16 v[80:83], v[156:159], v[200:203], v[80:83]
	v_mfma_f32_16x16x32_bf16 v[68:71], v[164:167], v[200:203], v[68:71]
	v_mfma_f32_16x16x32_bf16 v[128:131], v[160:163], v[176:179], v[128:131]
	v_mfma_f32_16x16x32_bf16 v[120:123], v[168:171], v[176:179], v[120:123]
	v_mfma_f32_16x16x32_bf16 v[112:115], v[160:163], v[184:187], v[112:115]
	v_mfma_f32_16x16x32_bf16 v[104:107], v[168:171], v[184:187], v[104:107]
	v_mfma_f32_16x16x32_bf16 v[96:99], v[160:163], v[192:195], v[96:99]
	v_mfma_f32_16x16x32_bf16 v[88:91], v[168:171], v[192:195], v[88:91]
	v_mfma_f32_16x16x32_bf16 v[80:83], v[160:163], v[204:207], v[80:83]
	v_mfma_f32_16x16x32_bf16 v[68:71], v[168:171], v[204:207], v[68:71]
	s_barrier
	s_setprio 0
	s_mov_b32 m0, s92
	ds_read_b128 v[172:175], v137 offset:16384
	ds_read_b128 v[176:179], v137 offset:17408
	ds_read_b128 v[180:183], v137 offset:18432
	ds_read_b128 v[184:187], v137 offset:19456
	ds_read_b128 v[188:191], v137 offset:20480
	ds_read_b128 v[192:195], v137 offset:21504
	ds_read_b128 v[200:203], v137 offset:22528
	ds_read_b128 v[204:207], v137 offset:23552
	buffer_load_dwordx4 v133, s[16:19], s57 offen lds
	s_mov_b32 m0, s93
	s_add_i32 s60, s57, 0x40000
	buffer_load_dwordx4 v135, s[16:19], s57 offen lds
	s_mov_b32 m0, s94
	s_nop 0
	buffer_load_dwordx4 v133, s[16:19], s60 offen lds
	s_mov_b32 m0, s95
	s_nop 0
	buffer_load_dwordx4 v135, s[16:19], s60 offen lds
	s_mov_b32 m0, s44
	s_nop 0
	buffer_load_dwordx4 v132, s[20:23], s59 offen lds
	s_waitcnt vmcnt(7)
	s_waitcnt lgkmcnt(0)
	s_setprio 1
	s_barrier
; #define PG8_WAIT_V(n) asm volatile("s_waitcnt vmcnt(" #n ")" ::: "memory")
; template <class Epi, bool ALIGN_EPI, bool SP2, class Hook>
; __device__ __forceinline__ void gemm_phase(LAS unsigned char* lds, const Gemm g, const StaticOrder& S, const Epi& E, Acc& acc, const bool fresh, const Hook& H, const int wave_id) {
;     ...
;         for (int t = t0; t < nt; t += 2) {
;             const bool last = (t == nt - 2);
;             const Src a1 = cA + (size_t)(t + 1) * kstep;
;             const Src a2 = last ? nA : cA + (size_t)(t + 2) * kstep, b2 = last ? nB : cB + (size_t)(t + 2) * kstep;
;             const Src a3 = a2 + kstep, b3 = b2 + kstep;
;             if (last && has_next) H(nxt);
;             if constexpr (SP2) {
;             PG8_TRIP_SP2(PG8_WAIT_V(8));
	v_mfma_f32_16x16x32_bf16 v[60:63], v[140:143], v[172:175], v[60:63]
	v_mfma_f32_16x16x32_bf16 v[52:55], v[148:151], v[172:175], v[52:55]
	v_mfma_f32_16x16x32_bf16 v[44:47], v[140:143], v[180:183], v[44:47]
	v_mfma_f32_16x16x32_bf16 v[36:39], v[148:151], v[180:183], v[36:39]
	v_mfma_f32_16x16x32_bf16 v[28:31], v[140:143], v[188:191], v[28:31]
	v_mfma_f32_16x16x32_bf16 v[20:23], v[148:151], v[188:191], v[20:23]
	v_mfma_f32_16x16x32_bf16 v[12:15], v[140:143], v[200:203], v[12:15]
	v_mfma_f32_16x16x32_bf16 v[2:5], v[148:151], v[200:203], v[4:7]
	v_mfma_f32_16x16x32_bf16 v[60:63], v[144:147], v[176:179], v[60:63]
	v_mfma_f32_16x16x32_bf16 v[52:55], v[152:155], v[176:179], v[52:55]
	v_mfma_f32_16x16x32_bf16 v[44:47], v[144:147], v[184:187], v[44:47]
	v_mfma_f32_16x16x32_bf16 v[36:39], v[152:155], v[184:187], v[36:39]
	v_mfma_f32_16x16x32_bf16 v[28:31], v[144:147], v[192:195], v[28:31]
	v_mfma_f32_16x16x32_bf16 v[20:23], v[152:155], v[192:195], v[20:23]
	v_mfma_f32_16x16x32_bf16 v[12:15], v[144:147], v[204:207], v[12:15]
	v_mfma_f32_16x16x32_bf16 v[2:5], v[152:155], v[204:207], v[2:5]
	v_mfma_f32_16x16x32_bf16 v[72:75], v[156:159], v[172:175], v[72:75]
	v_mfma_f32_16x16x32_bf16 v[56:59], v[164:167], v[172:175], v[56:59]
	v_mfma_f32_16x16x32_bf16 v[48:51], v[156:159], v[180:183], v[48:51]
	v_mfma_f32_16x16x32_bf16 v[40:43], v[164:167], v[180:183], v[40:43]
	v_mfma_f32_16x16x32_bf16 v[32:35], v[156:159], v[188:191], v[32:35]
	v_mfma_f32_16x16x32_bf16 v[24:27], v[164:167], v[188:191], v[24:27]
	v_mfma_f32_16x16x32_bf16 v[16:19], v[156:159], v[200:203], v[16:19]
	v_mfma_f32_16x16x32_bf16 v[6:9], v[164:167], v[200:203], v[8:11]
	v_mfma_f32_16x16x32_bf16 v[72:75], v[160:163], v[176:179], v[72:75]
	v_mfma_f32_16x16x32_bf16 v[56:59], v[168:171], v[176:179], v[56:59]
	v_mfma_f32_16x16x32_bf16 v[48:51], v[160:163], v[184:187], v[48:51]
	v_mfma_f32_16x16x32_bf16 v[40:43], v[168:171], v[184:187], v[40:43]
	v_mfma_f32_16x16x32_bf16 v[32:35], v[160:163], v[192:195], v[32:35]
	v_mfma_f32_16x16x32_bf16 v[24:27], v[168:171], v[192:195], v[24:27]
	v_mfma_f32_16x16x32_bf16 v[16:19], v[160:163], v[204:207], v[16:19]
	v_mfma_f32_16x16x32_bf16 v[8:11], v[168:171], v[204:207], v[6:9]
	s_barrier
	s_setprio 0
	s_mov_b32 m0, s36
	s_nop 0
	buffer_load_dwordx4 v134, s[20:23], s59 offen lds
	v_add_u32_e32 v140, 0x18000, v136
	v_add_u32_e32 v141, 0x1c000, v136
	ds_read_b128 v[142:145], v140
	ds_read_b128 v[146:149], v140 offset:1024
	ds_read_b128 v[150:153], v140 offset:2048
	ds_read_b128 v[154:157], v140 offset:3072
	ds_read_b128 v[158:161], v141
	ds_read_b128 v[162:165], v141 offset:1024
	ds_read_b128 v[166:169], v141 offset:2048
	ds_read_b128 v[170:173], v141 offset:3072
	s_add_i32 s59, s59, 0x40000
	s_mov_b32 m0, s37
	ds_read_b128 v[174:177], v137 offset:32768
	ds_read_b128 v[178:181], v137 offset:33792
	ds_read_b128 v[182:185], v137 offset:34816
	ds_read_b128 v[186:189], v137 offset:35840
	ds_read_b128 v[190:193], v137 offset:36864
	ds_read_b128 v[194:197], v137 offset:37888
	ds_read_b128 v[200:203], v137 offset:38912
	ds_read_b128 v[204:207], v137 offset:39936
	buffer_load_dwordx4 v132, s[20:23], s59 offen lds
	s_mov_b32 m0, s38
	s_nop 0
	buffer_load_dwordx4 v134, s[20:23], s59 offen lds
	s_waitcnt vmcnt(8)
	s_waitcnt lgkmcnt(0)
	s_setprio 1
	s_barrier
	v_mfma_f32_16x16x32_bf16 v[124:127], v[142:145], v[174:177], v[124:127]
	v_mfma_f32_16x16x32_bf16 v[116:119], v[150:153], v[174:177], v[116:119]
	v_mfma_f32_16x16x32_bf16 v[108:111], v[142:145], v[182:185], v[108:111]
	v_mfma_f32_16x16x32_bf16 v[100:103], v[150:153], v[182:185], v[100:103]
	v_mfma_f32_16x16x32_bf16 v[92:95], v[142:145], v[190:193], v[92:95]
	v_mfma_f32_16x16x32_bf16 v[84:87], v[150:153], v[190:193], v[84:87]
	v_mfma_f32_16x16x32_bf16 v[76:79], v[142:145], v[200:203], v[76:79]
	v_mfma_f32_16x16x32_bf16 v[64:67], v[150:153], v[200:203], v[64:67]
	v_mfma_f32_16x16x32_bf16 v[124:127], v[146:149], v[178:181], v[124:127]
	v_mfma_f32_16x16x32_bf16 v[116:119], v[154:157], v[178:181], v[116:119]
	v_mfma_f32_16x16x32_bf16 v[108:111], v[146:149], v[186:189], v[108:111]
	v_mfma_f32_16x16x32_bf16 v[100:103], v[154:157], v[186:189], v[100:103]
	v_mfma_f32_16x16x32_bf16 v[92:95], v[146:149], v[194:197], v[92:95]
	v_mfma_f32_16x16x32_bf16 v[84:87], v[154:157], v[194:197], v[84:87]
	v_mfma_f32_16x16x32_bf16 v[76:79], v[146:149], v[204:207], v[76:79]
	v_mfma_f32_16x16x32_bf16 v[64:67], v[154:157], v[204:207], v[64:67]
	v_mfma_f32_16x16x32_bf16 v[128:131], v[158:161], v[174:177], v[128:131]
	v_mfma_f32_16x16x32_bf16 v[120:123], v[166:169], v[174:177], v[120:123]
	v_mfma_f32_16x16x32_bf16 v[112:115], v[158:161], v[182:185], v[112:115]
	v_mfma_f32_16x16x32_bf16 v[104:107], v[166:169], v[182:185], v[104:107]
	v_mfma_f32_16x16x32_bf16 v[96:99], v[158:161], v[190:193], v[96:99]
	v_mfma_f32_16x16x32_bf16 v[88:91], v[166:169], v[190:193], v[88:91]
	v_mfma_f32_16x16x32_bf16 v[80:83], v[158:161], v[200:203], v[80:83]
	v_mfma_f32_16x16x32_bf16 v[68:71], v[166:169], v[200:203], v[68:71]
	v_mfma_f32_16x16x32_bf16 v[128:131], v[162:165], v[178:181], v[128:131]
	v_mfma_f32_16x16x32_bf16 v[120:123], v[170:173], v[178:181], v[120:123]
	v_mfma_f32_16x16x32_bf16 v[112:115], v[162:165], v[186:189], v[112:115]
	v_mfma_f32_16x16x32_bf16 v[104:107], v[170:173], v[186:189], v[104:107]
	v_mfma_f32_16x16x32_bf16 v[96:99], v[162:165], v[194:197], v[96:99]
	v_mfma_f32_16x16x32_bf16 v[88:91], v[170:173], v[194:197], v[88:91]
	v_mfma_f32_16x16x32_bf16 v[80:83], v[162:165], v[204:207], v[80:83]
	v_mfma_f32_16x16x32_bf16 v[68:71], v[170:173], v[204:207], v[68:71]
	s_barrier
; #define PG8_STAGE(bufoff, gbase, voff) do { const Src _g = (gbase); _Pragma("unroll") for (int _i = 0; _i < 2; ++_i) \
;         __builtin_amdgcn_raw_ptr_buffer_load_lds(_g.r, (LAS unsigned*)(lds + (bufoff) + ldsw + _i * 8192), 16, (voff)[_i], _g.o, 0, 0); } while (0)
; #define PG8_WAIT_V(n) asm volatile("s_waitcnt vmcnt(" #n ")" ::: "memory")
; template <class Epi, bool ALIGN_EPI, bool SP2, class Hook>
; __device__ __forceinline__ void gemm_phase(LAS unsigned char* lds, const Gemm g, const StaticOrder& S, const Epi& E, Acc& acc, const bool fresh, const Hook& H, const int wave_id) {
;     ...
;         for (int t = t0; t < nt; t += 2) {
;             const bool last = (t == nt - 2);
;             const Src a1 = cA + (size_t)(t + 1) * kstep;
;             const Src a2 = last ? nA : cA + (size_t)(t + 2) * kstep, b2 = last ? nB : cB + (size_t)(t + 2) * kstep;
;             const Src a3 = a2 + kstep, b3 = b2 + kstep;
;             if (last && has_next) H(nxt);
;             if constexpr (SP2) {
;             PG8_TRIP_SP2(PG8_WAIT_V(8));
;             } else {
;             PG8_LDB(B0, 0, 0); PG8_SCHED; PG8_LDA(At, 0, 0); PG8_STAGE(PG8_SA(1, 1), a1 + hstepA, voffA);
;             PG8_WAIT_L(8); PG8_BAR; PG8_WAIT_L(0); PG8_MMA(0, 0, At, B0); PG8_BAR; PG8_SCHED;
;             PG8_LDB(B1, 0, 1); PG8_STAGE(PG8_SB(0, 0), b2, voffB);
;             PG8_BAR; PG8_WAIT_L(0); PG8_MMA(0, 1, At, B1); PG8_BAR;
;             PG8_LDA(At, 0, 1); PG8_STAGE(PG8_SA(0, 0), a2, voffA);
;             PG8_BAR; PG8_WAIT_L(0); PG8_MMA(1, 0, At, B0); PG8_BAR; PG8_SCHED;
;             PG8_STAGE(PG8_SB(0, 1), b2 + hstep, voffB);
;             PG8_WAIT_V(6); PG8_BAR; PG8_MMA(1, 1, At, B1); PG8_BAR;
;             PG8_LDB(B0, 1, 0); PG8_SCHED; PG8_LDA(At, 1, 0); PG8_STAGE(PG8_SA(0, 1), a2 + hstepA, voffA);
;             PG8_WAIT_L(8); PG8_BAR; PG8_WAIT_L(0); PG8_MMA(0, 0, At, B0); PG8_BAR; PG8_SCHED;
;             PG8_LDB(B1, 1, 1); PG8_STAGE(PG8_SB(1, 0), b3, voffB);
;             PG8_BAR; PG8_WAIT_L(0); PG8_MMA(0, 1, At, B1); PG8_BAR;
;             PG8_LDA(At, 1, 1); PG8_STAGE(PG8_SA(1, 0), a3, voffA);
;             PG8_BAR; PG8_WAIT_L(0); PG8_MMA(1, 0, At, B0); PG8_BAR; PG8_SCHED;
;             PG8_STAGE(PG8_SB(1, 1), b3 + hstep, voffB);
;             PG8_WAIT_V(6); PG8_BAR; PG8_MMA(1, 1, At, B1); PG8_BAR;
;             }
;         }
;         if constexpr (ALIGN_EPI) { if (wr == 0) PG8_BAR; }
	s_setprio 0
	s_mov_b32 m0, s39
	s_or_b32 s59, s57, 0x80
	ds_read_b128 v[174:177], v137 offset:49152
	ds_read_b128 v[178:181], v137 offset:50176
	ds_read_b128 v[182:185], v137 offset:51200
	ds_read_b128 v[186:189], v137 offset:52224
	ds_read_b128 v[190:193], v137 offset:53248
	ds_read_b128 v[194:197], v137 offset:54272
	ds_read_b128 v[200:203], v137 offset:55296
	ds_read_b128 v[204:207], v137 offset:56320
	buffer_load_dwordx4 v133, s[16:19], s59 offen lds
	s_mov_b32 m0, s40
	s_add_i32 s57, s57, 0x40080
	buffer_load_dwordx4 v135, s[16:19], s59 offen lds
	s_mov_b32 m0, s43
	s_nop 0
	buffer_load_dwordx4 v133, s[16:19], s57 offen lds
	s_mov_b32 m0, s42
	s_nop 0
	buffer_load_dwordx4 v135, s[16:19], s57 offen lds
	s_mov_b32 m0, s41
	s_nop 0
	buffer_load_dwordx4 v132, s[20:23], s58 offen lds
	s_waitcnt vmcnt(7)
	s_waitcnt lgkmcnt(0)
	s_setprio 1
	s_barrier
	v_mfma_f32_16x16x32_bf16 v[60:63], v[142:145], v[174:177], v[60:63]
	v_mfma_f32_16x16x32_bf16 v[52:55], v[150:153], v[174:177], v[52:55]
	v_mfma_f32_16x16x32_bf16 v[44:47], v[142:145], v[182:185], v[44:47]
	v_mfma_f32_16x16x32_bf16 v[36:39], v[150:153], v[182:185], v[36:39]
	v_mfma_f32_16x16x32_bf16 v[28:31], v[142:145], v[190:193], v[28:31]
	v_mfma_f32_16x16x32_bf16 v[20:23], v[150:153], v[190:193], v[20:23]
	v_mfma_f32_16x16x32_bf16 v[12:15], v[142:145], v[200:203], v[12:15]
	v_mfma_f32_16x16x32_bf16 v[2:5], v[150:153], v[200:203], v[2:5]
	v_mfma_f32_16x16x32_bf16 v[60:63], v[146:149], v[178:181], v[60:63]
	v_mfma_f32_16x16x32_bf16 v[52:55], v[154:157], v[178:181], v[52:55]
	v_mfma_f32_16x16x32_bf16 v[44:47], v[146:149], v[186:189], v[44:47]
	v_mfma_f32_16x16x32_bf16 v[36:39], v[154:157], v[186:189], v[36:39]
	v_mfma_f32_16x16x32_bf16 v[28:31], v[146:149], v[194:197], v[28:31]
	v_mfma_f32_16x16x32_bf16 v[20:23], v[154:157], v[194:197], v[20:23]
	v_mfma_f32_16x16x32_bf16 v[12:15], v[146:149], v[204:207], v[12:15]
	v_mfma_f32_16x16x32_bf16 v[4:7], v[154:157], v[204:207], v[2:5]
	v_mfma_f32_16x16x32_bf16 v[72:75], v[158:161], v[174:177], v[72:75]
	v_mfma_f32_16x16x32_bf16 v[56:59], v[166:169], v[174:177], v[56:59]
	v_mfma_f32_16x16x32_bf16 v[48:51], v[158:161], v[182:185], v[48:51]
	v_mfma_f32_16x16x32_bf16 v[40:43], v[166:169], v[182:185], v[40:43]
	v_mfma_f32_16x16x32_bf16 v[32:35], v[158:161], v[190:193], v[32:35]
	v_mfma_f32_16x16x32_bf16 v[24:27], v[166:169], v[190:193], v[24:27]
	v_mfma_f32_16x16x32_bf16 v[16:19], v[158:161], v[200:203], v[16:19]
	v_mfma_f32_16x16x32_bf16 v[8:11], v[166:169], v[200:203], v[8:11]
	v_mfma_f32_16x16x32_bf16 v[72:75], v[162:165], v[178:181], v[72:75]
	v_mfma_f32_16x16x32_bf16 v[56:59], v[170:173], v[178:181], v[56:59]
	v_mfma_f32_16x16x32_bf16 v[48:51], v[162:165], v[186:189], v[48:51]
	v_mfma_f32_16x16x32_bf16 v[40:43], v[170:173], v[186:189], v[40:43]
	v_mfma_f32_16x16x32_bf16 v[32:35], v[162:165], v[194:197], v[32:35]
	v_mfma_f32_16x16x32_bf16 v[24:27], v[170:173], v[194:197], v[24:27]
	v_mfma_f32_16x16x32_bf16 v[16:19], v[162:165], v[204:207], v[16:19]
	v_mfma_f32_16x16x32_bf16 v[8:11], v[170:173], v[204:207], v[8:11]
	s_barrier
	s_setprio 0
	s_add_i32 s54, s54, 2
	s_addk_i32 s55, 0x100
	s_addk_i32 s56, 0x100
	s_cmp_gt_u32 s54, 13
	s_cbranch_scc0 .LBB0_1461
	s_mov_b32 m0, s33
	s_nop 0
	buffer_load_dwordx4 v134, s[20:23], s58 offen lds
	v_readlane_b32 s12, v251, 45
	v_readlane_b32 s13, v251, 46
	s_and_b64 vcc, exec, s[12:13]
	s_cbranch_vccz .LBB0_1464
	s_barrier

; #define PG8_WAIT_V(n) asm volatile("s_waitcnt vmcnt(" #n ")" ::: "memory")
; template <class Epi, bool ALIGN_EPI, bool SP2, class Hook>
; __device__ __forceinline__ void gemm_phase(LAS unsigned char* lds, const Gemm g, const StaticOrder& S, const Epi& E, Acc& acc, const bool fresh, const Hook& H, const int wave_id) {
;     ...
;         for (int t = t0; t < nt; t += 2) {
;             const bool last = (t == nt - 2);
;             const Src a1 = cA + (size_t)(t + 1) * kstep;
;             const Src a2 = last ? nA : cA + (size_t)(t + 2) * kstep, b2 = last ? nB : cB + (size_t)(t + 2) * kstep;
;             const Src a3 = a2 + kstep, b3 = b2 + kstep;
;             if (last && has_next) H(nxt);
;             if constexpr (SP2) {
;             PG8_TRIP_SP2(PG8_WAIT_V(8));
.LBB0_1572:
	s_add_i32 s100, s2, 0xfff40000
	v_add_u32_e32 v142, 0x10000, v161
	v_add_u32_e32 v163, 0x14000, v161
	ds_read_b128 v[130:133], v142
	ds_read_b128 v[134:137], v142 offset:1024
	ds_read_b128 v[138:141], v142 offset:2048
	ds_read_b128 v[142:145], v142 offset:3072
	ds_read_b128 v[146:149], v163
	ds_read_b128 v[150:153], v163 offset:1024
	ds_read_b128 v[154:157], v163 offset:2048
	ds_read_b128 v[164:167], v163 offset:3072
	s_add_i32 s16, s2, 0xfff40080
	s_cmp_eq_u32 s61, 40
	s_cselect_b32 s64, s57, s16
	s_cselect_b32 s17, s35, s9
	s_cselect_b32 s16, s34, s8
	s_cselect_b32 s19, s51, s53
	s_cselect_b32 s18, s50, s52
	s_cselect_b32 s62, s58, s3
	s_cselect_b32 s20, s10, s12
	s_cselect_b32 s21, s11, s13
	s_cselect_b32 s22, s30, s14
	s_cselect_b32 s23, s31, s15
	s_or_b32 s63, s64, 0x80
	s_mov_b32 m0, s33
	s_nop 0
	buffer_load_dwordx4 v159, s[12:15], s100 offen lds
	s_mov_b32 m0, s45
	ds_read_b128 v[168:171], v162
	ds_read_b128 v[172:175], v162 offset:1024
	ds_read_b128 v[176:179], v162 offset:2048
	ds_read_b128 v[180:183], v162 offset:3072
	ds_read_b128 v[184:187], v162 offset:4096
	ds_read_b128 v[188:191], v162 offset:5120
	ds_read_b128 v[192:195], v162 offset:6144
	ds_read_b128 v[200:203], v162 offset:7168
	buffer_load_dwordx4 v0, s[12:15], s2 offen lds
	s_mov_b32 m0, s46
	s_nop 0
	buffer_load_dwordx4 v159, s[12:15], s2 offen lds
	s_waitcnt vmcnt(8)
	s_waitcnt lgkmcnt(0)
	s_setprio 1
	s_barrier
	v_mfma_f32_16x16x32_bf16 v[126:129], v[130:133], v[168:171], v[126:129]
	v_mfma_f32_16x16x32_bf16 v[122:125], v[138:141], v[168:171], v[122:125]
	v_mfma_f32_16x16x32_bf16 v[110:113], v[130:133], v[176:179], v[110:113]
	v_mfma_f32_16x16x32_bf16 v[106:109], v[138:141], v[176:179], v[106:109]
	v_mfma_f32_16x16x32_bf16 v[94:97], v[130:133], v[184:187], v[94:97]
	v_mfma_f32_16x16x32_bf16 v[90:93], v[138:141], v[184:187], v[90:93]
	v_mfma_f32_16x16x32_bf16 v[78:81], v[130:133], v[192:195], v[78:81]
	v_mfma_f32_16x16x32_bf16 v[74:77], v[138:141], v[192:195], v[74:77]
	v_mfma_f32_16x16x32_bf16 v[126:129], v[134:137], v[172:175], v[126:129]
	v_mfma_f32_16x16x32_bf16 v[122:125], v[142:145], v[172:175], v[122:125]
	v_mfma_f32_16x16x32_bf16 v[110:113], v[134:137], v[180:183], v[110:113]
	v_mfma_f32_16x16x32_bf16 v[106:109], v[142:145], v[180:183], v[106:109]
	v_mfma_f32_16x16x32_bf16 v[94:97], v[134:137], v[188:191], v[94:97]
	v_mfma_f32_16x16x32_bf16 v[90:93], v[142:145], v[188:191], v[90:93]
	v_mfma_f32_16x16x32_bf16 v[78:81], v[134:137], v[200:203], v[78:81]
	v_mfma_f32_16x16x32_bf16 v[74:77], v[142:145], v[200:203], v[74:77]
	v_mfma_f32_16x16x32_bf16 v[118:121], v[146:149], v[168:171], v[118:121]
	v_mfma_f32_16x16x32_bf16 v[114:117], v[154:157], v[168:171], v[114:117]
	v_mfma_f32_16x16x32_bf16 v[102:105], v[146:149], v[176:179], v[102:105]
	v_mfma_f32_16x16x32_bf16 v[98:101], v[154:157], v[176:179], v[98:101]
	v_mfma_f32_16x16x32_bf16 v[86:89], v[146:149], v[184:187], v[86:89]
	v_mfma_f32_16x16x32_bf16 v[82:85], v[154:157], v[184:187], v[82:85]
	v_mfma_f32_16x16x32_bf16 v[70:73], v[146:149], v[192:195], v[70:73]
	v_mfma_f32_16x16x32_bf16 v[66:69], v[154:157], v[192:195], v[66:69]
	v_mfma_f32_16x16x32_bf16 v[118:121], v[150:153], v[172:175], v[118:121]
	v_mfma_f32_16x16x32_bf16 v[114:117], v[164:167], v[172:175], v[114:117]
	v_mfma_f32_16x16x32_bf16 v[102:105], v[150:153], v[180:183], v[102:105]
	v_mfma_f32_16x16x32_bf16 v[98:101], v[164:167], v[180:183], v[98:101]
	v_mfma_f32_16x16x32_bf16 v[86:89], v[150:153], v[188:191], v[86:89]
	v_mfma_f32_16x16x32_bf16 v[82:85], v[164:167], v[188:191], v[82:85]
	v_mfma_f32_16x16x32_bf16 v[70:73], v[150:153], v[200:203], v[70:73]
	v_mfma_f32_16x16x32_bf16 v[66:69], v[164:167], v[200:203], v[66:69]
	s_barrier
	s_setprio 0
	s_mov_b32 m0, s92
	ds_read_b128 v[168:171], v162 offset:16384
	ds_read_b128 v[172:175], v162 offset:17408
	ds_read_b128 v[176:179], v162 offset:18432
	ds_read_b128 v[180:183], v162 offset:19456
	ds_read_b128 v[184:187], v162 offset:20480
	ds_read_b128 v[188:191], v162 offset:21504
	ds_read_b128 v[192:195], v162 offset:22528
	ds_read_b128 v[200:203], v162 offset:23552
	buffer_load_dwordx4 v158, s[16:19], s62 offen lds
	s_mov_b32 m0, s93
	s_add_i32 s65, s62, 0xb0000
	buffer_load_dwordx4 v160, s[16:19], s62 offen lds
	s_mov_b32 m0, s94
	s_nop 0
	buffer_load_dwordx4 v158, s[16:19], s65 offen lds
	s_mov_b32 m0, s95
	s_nop 0
	buffer_load_dwordx4 v160, s[16:19], s65 offen lds
	s_mov_b32 m0, s44
	s_nop 0
	buffer_load_dwordx4 v0, s[20:23], s64 offen lds
	s_waitcnt vmcnt(7)
	s_waitcnt lgkmcnt(0)
	s_setprio 1
	s_barrier
	v_mfma_f32_16x16x32_bf16 v[62:65], v[130:133], v[168:171], v[62:65]
	v_mfma_f32_16x16x32_bf16 v[58:61], v[138:141], v[168:171], v[58:61]
	v_mfma_f32_16x16x32_bf16 v[46:49], v[130:133], v[176:179], v[46:49]
	v_mfma_f32_16x16x32_bf16 v[42:45], v[138:141], v[176:179], v[42:45]
	v_mfma_f32_16x16x32_bf16 v[30:33], v[130:133], v[184:187], v[30:33]
	v_mfma_f32_16x16x32_bf16 v[26:29], v[138:141], v[184:187], v[26:29]
	v_mfma_f32_16x16x32_bf16 v[14:17], v[130:133], v[192:195], v[14:17]
	v_mfma_f32_16x16x32_bf16 v[10:13], v[138:141], v[192:195], v[10:13]
	v_mfma_f32_16x16x32_bf16 v[62:65], v[134:137], v[172:175], v[62:65]
	v_mfma_f32_16x16x32_bf16 v[58:61], v[142:145], v[172:175], v[58:61]
	v_mfma_f32_16x16x32_bf16 v[46:49], v[134:137], v[180:183], v[46:49]
	v_mfma_f32_16x16x32_bf16 v[42:45], v[142:145], v[180:183], v[42:45]
	v_mfma_f32_16x16x32_bf16 v[30:33], v[134:137], v[188:191], v[30:33]
	v_mfma_f32_16x16x32_bf16 v[26:29], v[142:145], v[188:191], v[26:29]
	v_mfma_f32_16x16x32_bf16 v[14:17], v[134:137], v[200:203], v[14:17]
	v_mfma_f32_16x16x32_bf16 v[10:13], v[142:145], v[200:203], v[10:13]
	v_mfma_f32_16x16x32_bf16 v[54:57], v[146:149], v[168:171], v[54:57]
	v_mfma_f32_16x16x32_bf16 v[50:53], v[154:157], v[168:171], v[50:53]
	v_mfma_f32_16x16x32_bf16 v[38:41], v[146:149], v[176:179], v[38:41]
	v_mfma_f32_16x16x32_bf16 v[34:37], v[154:157], v[176:179], v[34:37]
	v_mfma_f32_16x16x32_bf16 v[22:25], v[146:149], v[184:187], v[22:25]
	v_mfma_f32_16x16x32_bf16 v[18:21], v[154:157], v[184:187], v[18:21]
	v_mfma_f32_16x16x32_bf16 v[6:9], v[146:149], v[192:195], v[6:9]
	v_mfma_f32_16x16x32_bf16 v[2:5], v[154:157], v[192:195], v[2:5]
	v_mfma_f32_16x16x32_bf16 v[54:57], v[150:153], v[172:175], v[54:57]
	v_mfma_f32_16x16x32_bf16 v[50:53], v[164:167], v[172:175], v[50:53]
	v_mfma_f32_16x16x32_bf16 v[38:41], v[150:153], v[180:183], v[38:41]
	v_mfma_f32_16x16x32_bf16 v[34:37], v[164:167], v[180:183], v[34:37]
	v_mfma_f32_16x16x32_bf16 v[22:25], v[150:153], v[188:191], v[22:25]
	v_mfma_f32_16x16x32_bf16 v[18:21], v[164:167], v[188:191], v[18:21]
	v_mfma_f32_16x16x32_bf16 v[6:9], v[150:153], v[200:203], v[6:9]
	v_mfma_f32_16x16x32_bf16 v[2:5], v[164:167], v[200:203], v[2:5]
	s_barrier
; #define PG8_STAGE(bufoff, gbase, voff) do { const Src _g = (gbase); _Pragma("unroll") for (int _i = 0; _i < 2; ++_i) \
;         __builtin_amdgcn_raw_ptr_buffer_load_lds(_g.r, (LAS unsigned*)(lds + (bufoff) + ldsw + _i * 8192), 16, (voff)[_i], _g.o, 0, 0); } while (0)
; #define PG8_WAIT_V(n) asm volatile("s_waitcnt vmcnt(" #n ")" ::: "memory")
; template <class Epi, bool ALIGN_EPI, bool SP2, class Hook>
; __device__ __forceinline__ void gemm_phase(LAS unsigned char* lds, const Gemm g, const StaticOrder& S, const Epi& E, Acc& acc, const bool fresh, const Hook& H, const int wave_id) {
;     ...
;         for (int t = t0; t < nt; t += 2) {
;             const bool last = (t == nt - 2);
;             const Src a1 = cA + (size_t)(t + 1) * kstep;
;             const Src a2 = last ? nA : cA + (size_t)(t + 2) * kstep, b2 = last ? nB : cB + (size_t)(t + 2) * kstep;
;             const Src a3 = a2 + kstep, b3 = b2 + kstep;
;             if (last && has_next) H(nxt);
;             if constexpr (SP2) {
;             PG8_TRIP_SP2(PG8_WAIT_V(8));
;             } else {
;             PG8_LDB(B0, 0, 0); PG8_SCHED; PG8_LDA(At, 0, 0); PG8_STAGE(PG8_SA(1, 1), a1 + hstepA, voffA);
;             PG8_WAIT_L(8); PG8_BAR; PG8_WAIT_L(0); PG8_MMA(0, 0, At, B0); PG8_BAR; PG8_SCHED;
;             PG8_LDB(B1, 0, 1); PG8_STAGE(PG8_SB(0, 0), b2, voffB);
;             PG8_BAR; PG8_WAIT_L(0); PG8_MMA(0, 1, At, B1); PG8_BAR;
;             PG8_LDA(At, 0, 1); PG8_STAGE(PG8_SA(0, 0), a2, voffA);
;             PG8_BAR; PG8_WAIT_L(0); PG8_MMA(1, 0, At, B0); PG8_BAR; PG8_SCHED;
;             PG8_STAGE(PG8_SB(0, 1), b2 + hstep, voffB);
;             PG8_WAIT_V(6); PG8_BAR; PG8_MMA(1, 1, At, B1); PG8_BAR;
;             PG8_LDB(B0, 1, 0); PG8_SCHED; PG8_LDA(At, 1, 0); PG8_STAGE(PG8_SA(0, 1), a2 + hstepA, voffA);
;             PG8_WAIT_L(8); PG8_BAR; PG8_WAIT_L(0); PG8_MMA(0, 0, At, B0); PG8_BAR; PG8_SCHED;
;             PG8_LDB(B1, 1, 1); PG8_STAGE(PG8_SB(1, 0), b3, voffB);
;             PG8_BAR; PG8_WAIT_L(0); PG8_MMA(0, 1, At, B1); PG8_BAR;
;             PG8_LDA(At, 1, 1); PG8_STAGE(PG8_SA(1, 0), a3, voffA);
;             PG8_BAR; PG8_WAIT_L(0); PG8_MMA(1, 0, At, B0); PG8_BAR; PG8_SCHED;
;             PG8_STAGE(PG8_SB(1, 1), b3 + hstep, voffB);
;             PG8_WAIT_V(6); PG8_BAR; PG8_MMA(1, 1, At, B1); PG8_BAR;
;             }
;         }
;         if constexpr (ALIGN_EPI) { if (wr == 0) PG8_BAR; }
	s_setprio 0
	s_mov_b32 m0, s36
	s_nop 0
	buffer_load_dwordx4 v159, s[20:23], s64 offen lds
	v_add_u32_e32 v142, 0x18000, v161
	v_add_u32_e32 v163, 0x1c000, v161
	ds_read_b128 v[130:133], v142
	ds_read_b128 v[134:137], v142 offset:1024
	ds_read_b128 v[138:141], v142 offset:2048
	ds_read_b128 v[142:145], v142 offset:3072
	ds_read_b128 v[146:149], v163
	ds_read_b128 v[150:153], v163 offset:1024
	ds_read_b128 v[154:157], v163 offset:2048
	ds_read_b128 v[164:167], v163 offset:3072
	s_add_i32 s64, s64, 0xc0000
	s_mov_b32 m0, s37
	ds_read_b128 v[168:171], v162 offset:32768
	ds_read_b128 v[172:175], v162 offset:33792
	ds_read_b128 v[176:179], v162 offset:34816
	ds_read_b128 v[180:183], v162 offset:35840
	ds_read_b128 v[184:187], v162 offset:36864
	ds_read_b128 v[188:191], v162 offset:37888
	ds_read_b128 v[192:195], v162 offset:38912
	ds_read_b128 v[200:203], v162 offset:39936
	buffer_load_dwordx4 v0, s[20:23], s64 offen lds
	s_mov_b32 m0, s38
	s_nop 0
	buffer_load_dwordx4 v159, s[20:23], s64 offen lds
	s_waitcnt vmcnt(8)
	s_waitcnt lgkmcnt(0)
	s_setprio 1
	s_barrier
	v_mfma_f32_16x16x32_bf16 v[126:129], v[130:133], v[168:171], v[126:129]
	v_mfma_f32_16x16x32_bf16 v[122:125], v[138:141], v[168:171], v[122:125]
	v_mfma_f32_16x16x32_bf16 v[110:113], v[130:133], v[176:179], v[110:113]
	v_mfma_f32_16x16x32_bf16 v[106:109], v[138:141], v[176:179], v[106:109]
	v_mfma_f32_16x16x32_bf16 v[94:97], v[130:133], v[184:187], v[94:97]
	v_mfma_f32_16x16x32_bf16 v[90:93], v[138:141], v[184:187], v[90:93]
	v_mfma_f32_16x16x32_bf16 v[78:81], v[130:133], v[192:195], v[78:81]
	v_mfma_f32_16x16x32_bf16 v[74:77], v[138:141], v[192:195], v[74:77]
	v_mfma_f32_16x16x32_bf16 v[126:129], v[134:137], v[172:175], v[126:129]
	v_mfma_f32_16x16x32_bf16 v[122:125], v[142:145], v[172:175], v[122:125]
	v_mfma_f32_16x16x32_bf16 v[110:113], v[134:137], v[180:183], v[110:113]
	v_mfma_f32_16x16x32_bf16 v[106:109], v[142:145], v[180:183], v[106:109]
	v_mfma_f32_16x16x32_bf16 v[94:97], v[134:137], v[188:191], v[94:97]
	v_mfma_f32_16x16x32_bf16 v[90:93], v[142:145], v[188:191], v[90:93]
	v_mfma_f32_16x16x32_bf16 v[78:81], v[134:137], v[200:203], v[78:81]
	v_mfma_f32_16x16x32_bf16 v[74:77], v[142:145], v[200:203], v[74:77]
	v_mfma_f32_16x16x32_bf16 v[118:121], v[146:149], v[168:171], v[118:121]
	v_mfma_f32_16x16x32_bf16 v[114:117], v[154:157], v[168:171], v[114:117]
	v_mfma_f32_16x16x32_bf16 v[102:105], v[146:149], v[176:179], v[102:105]
	v_mfma_f32_16x16x32_bf16 v[98:101], v[154:157], v[176:179], v[98:101]
	v_mfma_f32_16x16x32_bf16 v[86:89], v[146:149], v[184:187], v[86:89]
	v_mfma_f32_16x16x32_bf16 v[82:85], v[154:157], v[184:187], v[82:85]
	v_mfma_f32_16x16x32_bf16 v[70:73], v[146:149], v[192:195], v[70:73]
	v_mfma_f32_16x16x32_bf16 v[66:69], v[154:157], v[192:195], v[66:69]
	v_mfma_f32_16x16x32_bf16 v[118:121], v[150:153], v[172:175], v[118:121]
	v_mfma_f32_16x16x32_bf16 v[114:117], v[164:167], v[172:175], v[114:117]
	v_mfma_f32_16x16x32_bf16 v[102:105], v[150:153], v[180:183], v[102:105]
	v_mfma_f32_16x16x32_bf16 v[98:101], v[164:167], v[180:183], v[98:101]
	v_mfma_f32_16x16x32_bf16 v[86:89], v[150:153], v[188:191], v[86:89]
	v_mfma_f32_16x16x32_bf16 v[82:85], v[164:167], v[188:191], v[82:85]
	v_mfma_f32_16x16x32_bf16 v[70:73], v[150:153], v[200:203], v[70:73]
	v_mfma_f32_16x16x32_bf16 v[66:69], v[164:167], v[200:203], v[66:69]
	s_barrier
	s_setprio 0
	s_mov_b32 m0, s39
	s_or_b32 s64, s62, 0x80
	ds_read_b128 v[168:171], v162 offset:49152
	ds_read_b128 v[172:175], v162 offset:50176
	ds_read_b128 v[176:179], v162 offset:51200
	ds_read_b128 v[180:183], v162 offset:52224
	ds_read_b128 v[184:187], v162 offset:53248
	ds_read_b128 v[188:191], v162 offset:54272
	ds_read_b128 v[192:195], v162 offset:55296
	ds_read_b128 v[200:203], v162 offset:56320
	buffer_load_dwordx4 v158, s[16:19], s64 offen lds
	s_mov_b32 m0, s40
	s_add_i32 s62, s62, 0xb0080
	buffer_load_dwordx4 v160, s[16:19], s64 offen lds
	s_mov_b32 m0, s43
	s_nop 0
	buffer_load_dwordx4 v158, s[16:19], s62 offen lds
	s_mov_b32 m0, s42
	s_nop 0
	buffer_load_dwordx4 v160, s[16:19], s62 offen lds
	s_mov_b32 m0, s41
	s_nop 0
	buffer_load_dwordx4 v0, s[20:23], s63 offen lds
	s_waitcnt vmcnt(7)
	s_waitcnt lgkmcnt(0)
	s_setprio 1
	s_barrier
	v_mfma_f32_16x16x32_bf16 v[62:65], v[130:133], v[168:171], v[62:65]
	v_mfma_f32_16x16x32_bf16 v[58:61], v[138:141], v[168:171], v[58:61]
	v_mfma_f32_16x16x32_bf16 v[46:49], v[130:133], v[176:179], v[46:49]
	v_mfma_f32_16x16x32_bf16 v[42:45], v[138:141], v[176:179], v[42:45]
	v_mfma_f32_16x16x32_bf16 v[30:33], v[130:133], v[184:187], v[30:33]
	v_mfma_f32_16x16x32_bf16 v[26:29], v[138:141], v[184:187], v[26:29]
	v_mfma_f32_16x16x32_bf16 v[14:17], v[130:133], v[192:195], v[14:17]
	v_mfma_f32_16x16x32_bf16 v[10:13], v[138:141], v[192:195], v[10:13]
	v_mfma_f32_16x16x32_bf16 v[62:65], v[134:137], v[172:175], v[62:65]
	v_mfma_f32_16x16x32_bf16 v[58:61], v[142:145], v[172:175], v[58:61]
	v_mfma_f32_16x16x32_bf16 v[46:49], v[134:137], v[180:183], v[46:49]
	v_mfma_f32_16x16x32_bf16 v[42:45], v[142:145], v[180:183], v[42:45]
	v_mfma_f32_16x16x32_bf16 v[30:33], v[134:137], v[188:191], v[30:33]
	v_mfma_f32_16x16x32_bf16 v[26:29], v[142:145], v[188:191], v[26:29]
	v_mfma_f32_16x16x32_bf16 v[14:17], v[134:137], v[200:203], v[14:17]
	v_mfma_f32_16x16x32_bf16 v[10:13], v[142:145], v[200:203], v[10:13]
	v_mfma_f32_16x16x32_bf16 v[54:57], v[146:149], v[168:171], v[54:57]
	v_mfma_f32_16x16x32_bf16 v[50:53], v[154:157], v[168:171], v[50:53]
	v_mfma_f32_16x16x32_bf16 v[38:41], v[146:149], v[176:179], v[38:41]
	v_mfma_f32_16x16x32_bf16 v[34:37], v[154:157], v[176:179], v[34:37]
	v_mfma_f32_16x16x32_bf16 v[22:25], v[146:149], v[184:187], v[22:25]
	v_mfma_f32_16x16x32_bf16 v[18:21], v[154:157], v[184:187], v[18:21]
	v_mfma_f32_16x16x32_bf16 v[6:9], v[146:149], v[192:195], v[6:9]
	v_mfma_f32_16x16x32_bf16 v[2:5], v[154:157], v[192:195], v[2:5]
	v_mfma_f32_16x16x32_bf16 v[54:57], v[150:153], v[172:175], v[54:57]
	v_mfma_f32_16x16x32_bf16 v[50:53], v[164:167], v[172:175], v[50:53]
	v_mfma_f32_16x16x32_bf16 v[38:41], v[150:153], v[180:183], v[38:41]
	v_mfma_f32_16x16x32_bf16 v[34:37], v[164:167], v[180:183], v[34:37]
	v_mfma_f32_16x16x32_bf16 v[22:25], v[150:153], v[188:191], v[22:25]
	v_mfma_f32_16x16x32_bf16 v[18:21], v[164:167], v[188:191], v[18:21]
	v_mfma_f32_16x16x32_bf16 v[6:9], v[150:153], v[200:203], v[6:9]
	v_mfma_f32_16x16x32_bf16 v[2:5], v[164:167], v[200:203], v[2:5]
	s_barrier
	s_setprio 0
	s_add_i32 s61, s61, 2
	s_addk_i32 s2, 0x100
	s_addk_i32 s3, 0x100
	s_cmp_gt_u32 s61, 41
	s_cbranch_scc0 .LBB0_1572
	s_mov_b32 m0, s33
	s_nop 0
	buffer_load_dwordx4 v159, s[20:23], s63 offen lds
	v_readlane_b32 s2, v251, 45
	v_readlane_b32 s3, v251, 46
	s_and_b64 vcc, exec, s[2:3]
	s_cbranch_vccz .LBB0_1575
	s_barrier

; #define PG8_WAIT_V(n) asm volatile("s_waitcnt vmcnt(" #n ")" ::: "memory")
; template <class Epi, bool ALIGN_EPI, bool SP2, class Hook>
; __device__ __forceinline__ void gemm_phase(LAS unsigned char* lds, const Gemm g, const StaticOrder& S, const Epi& E, Acc& acc, const bool fresh, const Hook& H, const int wave_id) {
;     ...
;         for (int t = t0; t < nt; t += 2) {
;             const bool last = (t == nt - 2);
;             const Src a1 = cA + (size_t)(t + 1) * kstep;
;             const Src a2 = last ? nA : cA + (size_t)(t + 2) * kstep, b2 = last ? nB : cB + (size_t)(t + 2) * kstep;
;             const Src a3 = a2 + kstep, b3 = b2 + kstep;
;             if (last && has_next) H(nxt);
;             if constexpr (SP2) {
;             PG8_TRIP_SP2(PG8_WAIT_V(8));
.LBB0_1614:
	s_add_i32 s100, s2, 0xfff40000
	v_add_u32_e32 v0, 0x10000, v172
	ds_read_b128 v[130:133], v0
	ds_read_b128 v[134:137], v0 offset:1024
	ds_read_b128 v[138:141], v0 offset:2048
	ds_read_b128 v[142:145], v0 offset:3072
	v_add_u32_e32 v0, 0x14000, v172
	ds_read_b128 v[146:149], v0
	ds_read_b128 v[150:153], v0 offset:1024
	ds_read_b128 v[154:157], v0 offset:2048
	ds_read_b128 v[158:161], v0 offset:3072
	s_add_i32 s12, s2, 0xfff40080
	s_cmp_eq_u32 s59, 40
	s_cselect_b32 s62, s55, s12
	s_cselect_b32 s13, s31, s77
	s_cselect_b32 s12, s30, s76
	s_cselect_b32 s15, s35, s51
	s_cselect_b32 s14, s34, s50
	s_cselect_b32 s60, s56, s3
	s_cselect_b32 s16, s20, s8
	s_cselect_b32 s17, s21, s9
	s_cselect_b32 s18, s22, s10
	s_cselect_b32 s19, s23, s11
	s_or_b32 s61, s62, 0x80
	s_mov_b32 m0, s33
	s_nop 0
	buffer_load_dwordx4 v170, s[8:11], s100 offen lds
	s_mov_b32 m0, s45
	ds_read_b128 v[162:165], v173
	ds_read_b128 v[174:177], v173 offset:1024
	ds_read_b128 v[178:181], v173 offset:2048
	ds_read_b128 v[182:185], v173 offset:3072
	ds_read_b128 v[186:189], v173 offset:4096
	ds_read_b128 v[190:193], v173 offset:5120
	ds_read_b128 v[194:197], v173 offset:6144
	ds_read_b128 v[200:203], v173 offset:7168
	buffer_load_dwordx4 v168, s[8:11], s2 offen lds
	s_mov_b32 m0, s46
	s_nop 0
	buffer_load_dwordx4 v170, s[8:11], s2 offen lds
	s_waitcnt vmcnt(8)
	s_waitcnt lgkmcnt(0)
	s_setprio 1
	s_barrier
	v_mfma_f32_16x16x32_bf16 v[126:129], v[130:133], v[162:165], v[126:129]
	v_mfma_f32_16x16x32_bf16 v[122:125], v[138:141], v[162:165], v[122:125]
	v_mfma_f32_16x16x32_bf16 v[110:113], v[130:133], v[178:181], v[110:113]
	v_mfma_f32_16x16x32_bf16 v[106:109], v[138:141], v[178:181], v[106:109]
	v_mfma_f32_16x16x32_bf16 v[94:97], v[130:133], v[186:189], v[94:97]
	v_mfma_f32_16x16x32_bf16 v[90:93], v[138:141], v[186:189], v[90:93]
	v_mfma_f32_16x16x32_bf16 v[78:81], v[130:133], v[194:197], v[78:81]
	v_mfma_f32_16x16x32_bf16 v[74:77], v[138:141], v[194:197], v[74:77]
	v_mfma_f32_16x16x32_bf16 v[126:129], v[134:137], v[174:177], v[126:129]
	v_mfma_f32_16x16x32_bf16 v[122:125], v[142:145], v[174:177], v[122:125]
	v_mfma_f32_16x16x32_bf16 v[110:113], v[134:137], v[182:185], v[110:113]
	v_mfma_f32_16x16x32_bf16 v[106:109], v[142:145], v[182:185], v[106:109]
	v_mfma_f32_16x16x32_bf16 v[94:97], v[134:137], v[190:193], v[94:97]
	v_mfma_f32_16x16x32_bf16 v[90:93], v[142:145], v[190:193], v[90:93]
	v_mfma_f32_16x16x32_bf16 v[78:81], v[134:137], v[200:203], v[78:81]
	v_mfma_f32_16x16x32_bf16 v[74:77], v[142:145], v[200:203], v[74:77]
	v_mfma_f32_16x16x32_bf16 v[118:121], v[146:149], v[162:165], v[118:121]
	v_mfma_f32_16x16x32_bf16 v[114:117], v[154:157], v[162:165], v[114:117]
	v_mfma_f32_16x16x32_bf16 v[102:105], v[146:149], v[178:181], v[102:105]
	v_mfma_f32_16x16x32_bf16 v[98:101], v[154:157], v[178:181], v[98:101]
	v_mfma_f32_16x16x32_bf16 v[86:89], v[146:149], v[186:189], v[86:89]
	v_mfma_f32_16x16x32_bf16 v[82:85], v[154:157], v[186:189], v[82:85]
	v_mfma_f32_16x16x32_bf16 v[70:73], v[146:149], v[194:197], v[70:73]
	v_mfma_f32_16x16x32_bf16 v[66:69], v[154:157], v[194:197], v[66:69]
	v_mfma_f32_16x16x32_bf16 v[118:121], v[150:153], v[174:177], v[118:121]
	v_mfma_f32_16x16x32_bf16 v[114:117], v[158:161], v[174:177], v[114:117]
	v_mfma_f32_16x16x32_bf16 v[102:105], v[150:153], v[182:185], v[102:105]
	v_mfma_f32_16x16x32_bf16 v[98:101], v[158:161], v[182:185], v[98:101]
	v_mfma_f32_16x16x32_bf16 v[86:89], v[150:153], v[190:193], v[86:89]
	v_mfma_f32_16x16x32_bf16 v[82:85], v[158:161], v[190:193], v[82:85]
	v_mfma_f32_16x16x32_bf16 v[70:73], v[150:153], v[200:203], v[70:73]
	v_mfma_f32_16x16x32_bf16 v[66:69], v[158:161], v[200:203], v[66:69]
	s_barrier
	s_setprio 0
	s_mov_b32 m0, s92
	ds_read_b128 v[162:165], v173 offset:16384
	ds_read_b128 v[174:177], v173 offset:17408
	ds_read_b128 v[178:181], v173 offset:18432
	ds_read_b128 v[182:185], v173 offset:19456
	ds_read_b128 v[186:189], v173 offset:20480
	ds_read_b128 v[190:193], v173 offset:21504
	ds_read_b128 v[194:197], v173 offset:22528
	ds_read_b128 v[200:203], v173 offset:23552
	buffer_load_dwordx4 v169, s[12:15], s60 offen lds
	s_mov_b32 m0, s93
	s_add_i32 s63, s60, 0xb0000
	buffer_load_dwordx4 v171, s[12:15], s60 offen lds
	s_mov_b32 m0, s94
	s_nop 0
	buffer_load_dwordx4 v169, s[12:15], s63 offen lds
	s_mov_b32 m0, s95
	s_nop 0
	buffer_load_dwordx4 v171, s[12:15], s63 offen lds
	s_mov_b32 m0, s44
	s_nop 0
	buffer_load_dwordx4 v168, s[16:19], s62 offen lds
	s_waitcnt vmcnt(7)
	s_waitcnt lgkmcnt(0)
	s_setprio 1
	s_barrier
	v_mfma_f32_16x16x32_bf16 v[62:65], v[130:133], v[162:165], v[62:65]
	v_mfma_f32_16x16x32_bf16 v[58:61], v[138:141], v[162:165], v[58:61]
	v_mfma_f32_16x16x32_bf16 v[46:49], v[130:133], v[178:181], v[46:49]
	v_mfma_f32_16x16x32_bf16 v[42:45], v[138:141], v[178:181], v[42:45]
	v_mfma_f32_16x16x32_bf16 v[30:33], v[130:133], v[186:189], v[30:33]
	v_mfma_f32_16x16x32_bf16 v[26:29], v[138:141], v[186:189], v[26:29]
	v_mfma_f32_16x16x32_bf16 v[14:17], v[130:133], v[194:197], v[14:17]
	v_mfma_f32_16x16x32_bf16 v[10:13], v[138:141], v[194:197], v[10:13]
	v_mfma_f32_16x16x32_bf16 v[62:65], v[134:137], v[174:177], v[62:65]
	v_mfma_f32_16x16x32_bf16 v[58:61], v[142:145], v[174:177], v[58:61]
	v_mfma_f32_16x16x32_bf16 v[46:49], v[134:137], v[182:185], v[46:49]
	v_mfma_f32_16x16x32_bf16 v[42:45], v[142:145], v[182:185], v[42:45]
	v_mfma_f32_16x16x32_bf16 v[30:33], v[134:137], v[190:193], v[30:33]
	v_mfma_f32_16x16x32_bf16 v[26:29], v[142:145], v[190:193], v[26:29]
	v_mfma_f32_16x16x32_bf16 v[14:17], v[134:137], v[200:203], v[14:17]
	v_mfma_f32_16x16x32_bf16 v[10:13], v[142:145], v[200:203], v[10:13]
	v_mfma_f32_16x16x32_bf16 v[54:57], v[146:149], v[162:165], v[54:57]
	v_mfma_f32_16x16x32_bf16 v[50:53], v[154:157], v[162:165], v[50:53]
	v_mfma_f32_16x16x32_bf16 v[38:41], v[146:149], v[178:181], v[38:41]
	v_mfma_f32_16x16x32_bf16 v[34:37], v[154:157], v[178:181], v[34:37]
	v_mfma_f32_16x16x32_bf16 v[22:25], v[146:149], v[186:189], v[22:25]
	v_mfma_f32_16x16x32_bf16 v[18:21], v[154:157], v[186:189], v[18:21]
	v_mfma_f32_16x16x32_bf16 v[6:9], v[146:149], v[194:197], v[6:9]
	v_mfma_f32_16x16x32_bf16 v[2:5], v[154:157], v[194:197], v[2:5]
	v_mfma_f32_16x16x32_bf16 v[54:57], v[150:153], v[174:177], v[54:57]
	v_mfma_f32_16x16x32_bf16 v[50:53], v[158:161], v[174:177], v[50:53]
	v_mfma_f32_16x16x32_bf16 v[38:41], v[150:153], v[182:185], v[38:41]
	v_mfma_f32_16x16x32_bf16 v[34:37], v[158:161], v[182:185], v[34:37]
	v_mfma_f32_16x16x32_bf16 v[22:25], v[150:153], v[190:193], v[22:25]
	v_mfma_f32_16x16x32_bf16 v[18:21], v[158:161], v[190:193], v[18:21]
	v_mfma_f32_16x16x32_bf16 v[6:9], v[150:153], v[200:203], v[6:9]
	v_mfma_f32_16x16x32_bf16 v[2:5], v[158:161], v[200:203], v[2:5]
	s_barrier
; #define PG8_STAGE(bufoff, gbase, voff) do { const Src _g = (gbase); _Pragma("unroll") for (int _i = 0; _i < 2; ++_i) \
;         __builtin_amdgcn_raw_ptr_buffer_load_lds(_g.r, (LAS unsigned*)(lds + (bufoff) + ldsw + _i * 8192), 16, (voff)[_i], _g.o, 0, 0); } while (0)
; #define PG8_WAIT_V(n) asm volatile("s_waitcnt vmcnt(" #n ")" ::: "memory")
; template <class Epi, bool ALIGN_EPI, bool SP2, class Hook>
; __device__ __forceinline__ void gemm_phase(LAS unsigned char* lds, const Gemm g, const StaticOrder& S, const Epi& E, Acc& acc, const bool fresh, const Hook& H, const int wave_id) {
;     ...
;         for (int t = t0; t < nt; t += 2) {
;             const bool last = (t == nt - 2);
;             const Src a1 = cA + (size_t)(t + 1) * kstep;
;             const Src a2 = last ? nA : cA + (size_t)(t + 2) * kstep, b2 = last ? nB : cB + (size_t)(t + 2) * kstep;
;             const Src a3 = a2 + kstep, b3 = b2 + kstep;
;             if (last && has_next) H(nxt);
;             if constexpr (SP2) {
;             PG8_TRIP_SP2(PG8_WAIT_V(8));
;             } else {
;             PG8_LDB(B0, 0, 0); PG8_SCHED; PG8_LDA(At, 0, 0); PG8_STAGE(PG8_SA(1, 1), a1 + hstepA, voffA);
;             PG8_WAIT_L(8); PG8_BAR; PG8_WAIT_L(0); PG8_MMA(0, 0, At, B0); PG8_BAR; PG8_SCHED;
;             PG8_LDB(B1, 0, 1); PG8_STAGE(PG8_SB(0, 0), b2, voffB);
;             PG8_BAR; PG8_WAIT_L(0); PG8_MMA(0, 1, At, B1); PG8_BAR;
;             PG8_LDA(At, 0, 1); PG8_STAGE(PG8_SA(0, 0), a2, voffA);
;             PG8_BAR; PG8_WAIT_L(0); PG8_MMA(1, 0, At, B0); PG8_BAR; PG8_SCHED;
;             PG8_STAGE(PG8_SB(0, 1), b2 + hstep, voffB);
;             PG8_WAIT_V(6); PG8_BAR; PG8_MMA(1, 1, At, B1); PG8_BAR;
;             PG8_LDB(B0, 1, 0); PG8_SCHED; PG8_LDA(At, 1, 0); PG8_STAGE(PG8_SA(0, 1), a2 + hstepA, voffA);
;             PG8_WAIT_L(8); PG8_BAR; PG8_WAIT_L(0); PG8_MMA(0, 0, At, B0); PG8_BAR; PG8_SCHED;
;             PG8_LDB(B1, 1, 1); PG8_STAGE(PG8_SB(1, 0), b3, voffB);
;             PG8_BAR; PG8_WAIT_L(0); PG8_MMA(0, 1, At, B1); PG8_BAR;
;             PG8_LDA(At, 1, 1); PG8_STAGE(PG8_SA(1, 0), a3, voffA);
;             PG8_BAR; PG8_WAIT_L(0); PG8_MMA(1, 0, At, B0); PG8_BAR; PG8_SCHED;
;             PG8_STAGE(PG8_SB(1, 1), b3 + hstep, voffB);
;             PG8_WAIT_V(6); PG8_BAR; PG8_MMA(1, 1, At, B1); PG8_BAR;
;             }
;         }
;         if constexpr (ALIGN_EPI) { if (wr == 0) PG8_BAR; }
	s_setprio 0
	s_mov_b32 m0, s36
	s_nop 0
	buffer_load_dwordx4 v170, s[16:19], s62 offen lds
	v_add_u32_e32 v0, 0x18000, v172
	ds_read_b128 v[130:133], v0
	ds_read_b128 v[134:137], v0 offset:1024
	ds_read_b128 v[138:141], v0 offset:2048
	ds_read_b128 v[142:145], v0 offset:3072
	v_add_u32_e32 v0, 0x1c000, v172
	ds_read_b128 v[146:149], v0
	ds_read_b128 v[150:153], v0 offset:1024
	ds_read_b128 v[154:157], v0 offset:2048
	ds_read_b128 v[158:161], v0 offset:3072
	s_add_i32 s62, s62, 0xc0000
	s_mov_b32 m0, s37
	ds_read_b128 v[162:165], v173 offset:32768
	ds_read_b128 v[174:177], v173 offset:33792
	ds_read_b128 v[178:181], v173 offset:34816
	ds_read_b128 v[182:185], v173 offset:35840
	ds_read_b128 v[186:189], v173 offset:36864
	ds_read_b128 v[190:193], v173 offset:37888
	ds_read_b128 v[194:197], v173 offset:38912
	ds_read_b128 v[200:203], v173 offset:39936
	buffer_load_dwordx4 v168, s[16:19], s62 offen lds
	s_mov_b32 m0, s38
	s_nop 0
	buffer_load_dwordx4 v170, s[16:19], s62 offen lds
	s_waitcnt vmcnt(8)
	s_waitcnt lgkmcnt(0)
	s_setprio 1
	s_barrier
	v_mfma_f32_16x16x32_bf16 v[126:129], v[130:133], v[162:165], v[126:129]
	v_mfma_f32_16x16x32_bf16 v[122:125], v[138:141], v[162:165], v[122:125]
	v_mfma_f32_16x16x32_bf16 v[110:113], v[130:133], v[178:181], v[110:113]
	v_mfma_f32_16x16x32_bf16 v[106:109], v[138:141], v[178:181], v[106:109]
	v_mfma_f32_16x16x32_bf16 v[94:97], v[130:133], v[186:189], v[94:97]
	v_mfma_f32_16x16x32_bf16 v[90:93], v[138:141], v[186:189], v[90:93]
	v_mfma_f32_16x16x32_bf16 v[78:81], v[130:133], v[194:197], v[78:81]
	v_mfma_f32_16x16x32_bf16 v[74:77], v[138:141], v[194:197], v[74:77]
	v_mfma_f32_16x16x32_bf16 v[126:129], v[134:137], v[174:177], v[126:129]
	v_mfma_f32_16x16x32_bf16 v[122:125], v[142:145], v[174:177], v[122:125]
	v_mfma_f32_16x16x32_bf16 v[110:113], v[134:137], v[182:185], v[110:113]
	v_mfma_f32_16x16x32_bf16 v[106:109], v[142:145], v[182:185], v[106:109]
	v_mfma_f32_16x16x32_bf16 v[94:97], v[134:137], v[190:193], v[94:97]
	v_mfma_f32_16x16x32_bf16 v[90:93], v[142:145], v[190:193], v[90:93]
	v_mfma_f32_16x16x32_bf16 v[78:81], v[134:137], v[200:203], v[78:81]
	v_mfma_f32_16x16x32_bf16 v[74:77], v[142:145], v[200:203], v[74:77]
	v_mfma_f32_16x16x32_bf16 v[118:121], v[146:149], v[162:165], v[118:121]
	v_mfma_f32_16x16x32_bf16 v[114:117], v[154:157], v[162:165], v[114:117]
	v_mfma_f32_16x16x32_bf16 v[102:105], v[146:149], v[178:181], v[102:105]
	v_mfma_f32_16x16x32_bf16 v[98:101], v[154:157], v[178:181], v[98:101]
	v_mfma_f32_16x16x32_bf16 v[86:89], v[146:149], v[186:189], v[86:89]
	v_mfma_f32_16x16x32_bf16 v[82:85], v[154:157], v[186:189], v[82:85]
	v_mfma_f32_16x16x32_bf16 v[70:73], v[146:149], v[194:197], v[70:73]
	v_mfma_f32_16x16x32_bf16 v[66:69], v[154:157], v[194:197], v[66:69]
	v_mfma_f32_16x16x32_bf16 v[118:121], v[150:153], v[174:177], v[118:121]
	v_mfma_f32_16x16x32_bf16 v[114:117], v[158:161], v[174:177], v[114:117]
	v_mfma_f32_16x16x32_bf16 v[102:105], v[150:153], v[182:185], v[102:105]
	v_mfma_f32_16x16x32_bf16 v[98:101], v[158:161], v[182:185], v[98:101]
	v_mfma_f32_16x16x32_bf16 v[86:89], v[150:153], v[190:193], v[86:89]
	v_mfma_f32_16x16x32_bf16 v[82:85], v[158:161], v[190:193], v[82:85]
	v_mfma_f32_16x16x32_bf16 v[70:73], v[150:153], v[200:203], v[70:73]
	v_mfma_f32_16x16x32_bf16 v[66:69], v[158:161], v[200:203], v[66:69]
	s_barrier
	s_setprio 0
	s_mov_b32 m0, s39
	s_or_b32 s62, s60, 0x80
	ds_read_b128 v[162:165], v173 offset:49152
	ds_read_b128 v[174:177], v173 offset:50176
	ds_read_b128 v[178:181], v173 offset:51200
	ds_read_b128 v[182:185], v173 offset:52224
	ds_read_b128 v[186:189], v173 offset:53248
	ds_read_b128 v[190:193], v173 offset:54272
	ds_read_b128 v[194:197], v173 offset:55296
	ds_read_b128 v[200:203], v173 offset:56320
	buffer_load_dwordx4 v169, s[12:15], s62 offen lds
	s_mov_b32 m0, s40
	s_add_i32 s60, s60, 0xb0080
	buffer_load_dwordx4 v171, s[12:15], s62 offen lds
	s_mov_b32 m0, s43
	s_nop 0
	buffer_load_dwordx4 v169, s[12:15], s60 offen lds
	s_mov_b32 m0, s42
	s_nop 0
	buffer_load_dwordx4 v171, s[12:15], s60 offen lds
	s_mov_b32 m0, s41
	s_nop 0
	buffer_load_dwordx4 v168, s[16:19], s61 offen lds
	s_waitcnt vmcnt(7)
	s_waitcnt lgkmcnt(0)
	s_setprio 1
	s_barrier
	v_mfma_f32_16x16x32_bf16 v[62:65], v[130:133], v[162:165], v[62:65]
	v_mfma_f32_16x16x32_bf16 v[58:61], v[138:141], v[162:165], v[58:61]
	v_mfma_f32_16x16x32_bf16 v[46:49], v[130:133], v[178:181], v[46:49]
	v_mfma_f32_16x16x32_bf16 v[42:45], v[138:141], v[178:181], v[42:45]
	v_mfma_f32_16x16x32_bf16 v[30:33], v[130:133], v[186:189], v[30:33]
	v_mfma_f32_16x16x32_bf16 v[26:29], v[138:141], v[186:189], v[26:29]
	v_mfma_f32_16x16x32_bf16 v[14:17], v[130:133], v[194:197], v[14:17]
	v_mfma_f32_16x16x32_bf16 v[10:13], v[138:141], v[194:197], v[10:13]
	v_mfma_f32_16x16x32_bf16 v[62:65], v[134:137], v[174:177], v[62:65]
	v_mfma_f32_16x16x32_bf16 v[58:61], v[142:145], v[174:177], v[58:61]
	v_mfma_f32_16x16x32_bf16 v[46:49], v[134:137], v[182:185], v[46:49]
	v_mfma_f32_16x16x32_bf16 v[42:45], v[142:145], v[182:185], v[42:45]
	v_mfma_f32_16x16x32_bf16 v[30:33], v[134:137], v[190:193], v[30:33]
	v_mfma_f32_16x16x32_bf16 v[26:29], v[142:145], v[190:193], v[26:29]
	v_mfma_f32_16x16x32_bf16 v[14:17], v[134:137], v[200:203], v[14:17]
	v_mfma_f32_16x16x32_bf16 v[10:13], v[142:145], v[200:203], v[10:13]
	v_mfma_f32_16x16x32_bf16 v[54:57], v[146:149], v[162:165], v[54:57]
	v_mfma_f32_16x16x32_bf16 v[50:53], v[154:157], v[162:165], v[50:53]
	v_mfma_f32_16x16x32_bf16 v[38:41], v[146:149], v[178:181], v[38:41]
	v_mfma_f32_16x16x32_bf16 v[34:37], v[154:157], v[178:181], v[34:37]
	v_mfma_f32_16x16x32_bf16 v[22:25], v[146:149], v[186:189], v[22:25]
	v_mfma_f32_16x16x32_bf16 v[18:21], v[154:157], v[186:189], v[18:21]
	v_mfma_f32_16x16x32_bf16 v[6:9], v[146:149], v[194:197], v[6:9]
	v_mfma_f32_16x16x32_bf16 v[2:5], v[154:157], v[194:197], v[2:5]
	v_mfma_f32_16x16x32_bf16 v[54:57], v[150:153], v[174:177], v[54:57]
	v_mfma_f32_16x16x32_bf16 v[50:53], v[158:161], v[174:177], v[50:53]
	v_mfma_f32_16x16x32_bf16 v[38:41], v[150:153], v[182:185], v[38:41]
	v_mfma_f32_16x16x32_bf16 v[34:37], v[158:161], v[182:185], v[34:37]
	v_mfma_f32_16x16x32_bf16 v[22:25], v[150:153], v[190:193], v[22:25]
	v_mfma_f32_16x16x32_bf16 v[18:21], v[158:161], v[190:193], v[18:21]
	v_mfma_f32_16x16x32_bf16 v[6:9], v[150:153], v[200:203], v[6:9]
	v_mfma_f32_16x16x32_bf16 v[2:5], v[158:161], v[200:203], v[2:5]
	s_barrier
	s_setprio 0
	s_add_i32 s59, s59, 2
	s_addk_i32 s2, 0x100
	s_addk_i32 s3, 0x100
	s_cmp_gt_u32 s59, 41
	s_cbranch_scc0 .LBB0_1614
	s_mov_b32 m0, s33
	s_nop 0
	buffer_load_dwordx4 v170, s[16:19], s61 offen lds
	v_readlane_b32 s2, v251, 45
	v_readlane_b32 s3, v251, 46
	s_and_b64 vcc, exec, s[2:3]
	s_cbranch_vccz .LBB0_1617
	s_barrier
